# v8 + DPP row reductions in q/k norm loops + barrier followers poll cross-XCC generation word directly
# speedup vs baseline: 1.0141x; 1.0141x over previous
; DI unsigned xb_ld(unsigned* p) { return __hip_atomic_load(p, __ATOMIC_RELAXED, __HIP_MEMORY_SCOPE_AGENT); }
; DI unsigned xb_add(unsigned* p, unsigned v) { return __hip_atomic_fetch_add(p, v, __ATOMIC_RELAXED, __HIP_MEMORY_SCOPE_AGENT); }
; #define XB_SPIN(cond, bar) do { unsigned _sp = 0; while (cond) { __builtin_amdgcn_s_sleep(1); \
;     if ((++_sp & 255u) == 0u) { if (xb_ld(&(bar)[XB_TMO])) break; if (_sp > XB_SPIN_CAP) { atomicAdd(&(bar)[XB_TMO], 1u); break; } } } } while (0)
; DI void xcd_barrier(char* ws_, LAS unsigned char* lds_, int wv_) {
;     ...
;     const unsigned old = xb_add(&bar[XB_XSUB(x)], 1u);
;     const unsigned gen = old / nloc;
;     if (old + 1u == (gen + 1u) * nloc) {
;       __builtin_amdgcn_fence(__ATOMIC_RELEASE, "agent");
;       asm volatile("s_waitcnt vmcnt(0)" ::: "memory");
;       const unsigned og = xb_add(&bar[XB_TOP], 1u);
;       const unsigned tg = og / nx;
;       if (og + 1u == (tg + 1u) * nx) xb_add(&bar[XB_TOPGEN], 1u);
;       else XB_SPIN(xb_ld(&bar[XB_TOPGEN]) == tg, bar);
;       __builtin_amdgcn_fence(__ATOMIC_ACQUIRE, "agent");
;       xb_add(&bar[XB_XGEN(x)], 1u);
;       asm volatile("s_waitcnt vmcnt(0)" ::: "memory");
;     } else {
;       XB_SPIN(xb_ld(&bar[XB_XGEN(x)]) == gen, bar);
.LBB0_1387:
	s_lshl_b32 s2, s38, 8
	s_add_u32 s23, s36, s2
	s_addc_u32 s22, s37, 0
	v_mov_b32_e32 v1, s23
	v_add_co_u32_e32 v4, vcc, 0x1000, v1
	v_mov_b32_e32 v1, s22
	s_nop 0
	v_addc_co_u32_e32 v5, vcc, 0, v1, vcc
	v_mov_b32_e32 v1, 1
	flat_atomic_add v1, v[4:5], v1 offset:1024 sc0
	v_cvt_f32_u32_e32 v3, v2
	v_sub_u32_e32 v4, 0, v2
	v_rcp_iflag_f32_e32 v3, v3
	s_nop 0
	v_mul_f32_e32 v3, 0x4f7ffffe, v3
	v_cvt_u32_f32_e32 v3, v3
	v_mul_lo_u32 v4, v4, v3
	v_mul_hi_u32 v4, v3, v4
	v_add_u32_e32 v3, v3, v4
	s_waitcnt vmcnt(0) lgkmcnt(0)
	v_mul_hi_u32 v3, v1, v3
	v_mul_lo_u32 v5, v3, v2
	v_add_u32_e32 v4, 1, v1
	v_sub_u32_e32 v1, v1, v5
	v_add_u32_e32 v6, 1, v3
	v_cmp_ge_u32_e32 vcc, v1, v2
	v_sub_u32_e32 v5, v1, v2
	s_nop 0
	v_cndmask_b32_e32 v3, v3, v6, vcc
	v_cndmask_b32_e32 v1, v1, v5, vcc
	v_add_u32_e32 v5, 1, v3
	v_cmp_ge_u32_e32 vcc, v1, v2
	s_nop 1
	v_cndmask_b32_e32 v1, v3, v5, vcc
	v_mad_u64_u32 v[2:3], s[2:3], v2, v1, v[2:3]
	v_cmp_ne_u32_e32 vcc, v4, v2
	s_and_saveexec_b64 s[2:3], vcc
	s_xor_b64 s[2:3], exec, s[2:3]
	s_cbranch_execz .LBB0_1400
	s_add_u32 s6, s36, 0x3500
	s_addc_u32 s7, s37, 0
	v_mov_b32_e32 v2, s6
	v_mov_b32_e32 v3, s7
	flat_load_dword v0, v[2:3] sc1
	s_waitcnt vmcnt(0) lgkmcnt(0)
	v_cmp_eq_u32_e32 vcc, v0, v1
	s_and_saveexec_b64 s[4:5], vcc
	s_cbranch_execz .LBB0_1399
	s_mov_b32 s24, 1
	s_mov_b64 s[8:9], 0
	s_branch .LBB0_1391

; DI unsigned xb_ld(unsigned* p) { return __hip_atomic_load(p, __ATOMIC_RELAXED, __HIP_MEMORY_SCOPE_AGENT); }
; DI unsigned xb_add(unsigned* p, unsigned v) { return __hip_atomic_fetch_add(p, v, __ATOMIC_RELAXED, __HIP_MEMORY_SCOPE_AGENT); }
; #define XB_SPIN(cond, bar) do { unsigned _sp = 0; while (cond) { __builtin_amdgcn_s_sleep(1); \
;     if ((++_sp & 255u) == 0u) { if (xb_ld(&(bar)[XB_TMO])) break; if (_sp > XB_SPIN_CAP) { atomicAdd(&(bar)[XB_TMO], 1u); break; } } } } while (0)
; DI void xcd_barrier(char* ws_, LAS unsigned char* lds_, int wv_) {
;     ...
;     const unsigned old = xb_add(&bar[XB_XSUB(x)], 1u);
;     const unsigned gen = old / nloc;
;     if (old + 1u == (gen + 1u) * nloc) {
;       __builtin_amdgcn_fence(__ATOMIC_RELEASE, "agent");
;       asm volatile("s_waitcnt vmcnt(0)" ::: "memory");
;       const unsigned og = xb_add(&bar[XB_TOP], 1u);
;       const unsigned tg = og / nx;
;       if (og + 1u == (tg + 1u) * nx) xb_add(&bar[XB_TOPGEN], 1u);
;       else XB_SPIN(xb_ld(&bar[XB_TOPGEN]) == tg, bar);
;       __builtin_amdgcn_fence(__ATOMIC_ACQUIRE, "agent");
;       xb_add(&bar[XB_XGEN(x)], 1u);
;       asm volatile("s_waitcnt vmcnt(0)" ::: "memory");
;     } else {
;       XB_SPIN(xb_ld(&bar[XB_XGEN(x)]) == gen, bar);
.LBB0_1453:
	s_lshl_b32 s2, s34, 8
	s_add_u32 s23, s58, s2
	s_addc_u32 s22, s59, 0
	v_mov_b32_e32 v1, s23
	v_add_co_u32_e32 v6, vcc, 0x1000, v1
	v_mov_b32_e32 v1, s22
	s_nop 0
	v_addc_co_u32_e32 v7, vcc, 0, v1, vcc
	flat_atomic_add v3, v[6:7], v225 offset:1024 sc0
	v_cvt_f32_u32_e32 v1, v4
	v_sub_u32_e32 v5, 0, v4
	v_rcp_iflag_f32_e32 v1, v1
	s_nop 0
	v_mul_f32_e32 v1, 0x4f7ffffe, v1
	v_cvt_u32_f32_e32 v1, v1
	v_mul_lo_u32 v5, v5, v1
	v_mul_hi_u32 v5, v1, v5
	v_add_u32_e32 v1, v1, v5
	s_waitcnt vmcnt(0) lgkmcnt(0)
	v_mul_hi_u32 v1, v3, v1
	v_mul_lo_u32 v5, v1, v4
	v_sub_u32_e32 v5, v3, v5
	v_cmp_ge_u32_e32 vcc, v5, v4
	v_add_u32_e32 v6, 1, v1
	v_add_u32_e32 v3, 1, v3
	v_cndmask_b32_e32 v1, v1, v6, vcc
	v_sub_u32_e32 v6, v5, v4
	v_cndmask_b32_e32 v5, v5, v6, vcc
	v_cmp_ge_u32_e32 vcc, v5, v4
	v_add_u32_e32 v5, 1, v1
	s_nop 0
	v_cndmask_b32_e32 v1, v1, v5, vcc
	v_mad_u64_u32 v[4:5], s[2:3], v4, v1, v[4:5]
	v_cmp_ne_u32_e32 vcc, v3, v4
	s_and_saveexec_b64 s[2:3], vcc
	s_xor_b64 s[2:3], exec, s[2:3]
	s_cbranch_execz .LBB0_1466
	s_add_u32 s6, s58, 0x3500
	s_addc_u32 s7, s59, 0
	v_mov_b32_e32 v2, s6
	v_mov_b32_e32 v3, s7
	flat_load_dword v2, v[2:3] sc1
	s_waitcnt vmcnt(0) lgkmcnt(0)
	v_cmp_eq_u32_e32 vcc, v2, v1
	s_and_saveexec_b64 s[4:5], vcc
	s_cbranch_execz .LBB0_1465
	s_mov_b32 s24, 1
	s_mov_b64 s[8:9], 0
	s_branch .LBB0_1457

; DI unsigned xb_ld(unsigned* p) { return __hip_atomic_load(p, __ATOMIC_RELAXED, __HIP_MEMORY_SCOPE_AGENT); }
; DI unsigned xb_add(unsigned* p, unsigned v) { return __hip_atomic_fetch_add(p, v, __ATOMIC_RELAXED, __HIP_MEMORY_SCOPE_AGENT); }
; #define XB_SPIN(cond, bar) do { unsigned _sp = 0; while (cond) { __builtin_amdgcn_s_sleep(1); \
;     if ((++_sp & 255u) == 0u) { if (xb_ld(&(bar)[XB_TMO])) break; if (_sp > XB_SPIN_CAP) { atomicAdd(&(bar)[XB_TMO], 1u); break; } } } } while (0)
; DI void xcd_barrier(char* ws_, LAS unsigned char* lds_, int wv_) {
;     ...
;     const unsigned old = xb_add(&bar[XB_XSUB(x)], 1u);
;     const unsigned gen = old / nloc;
;     if (old + 1u == (gen + 1u) * nloc) {
;       __builtin_amdgcn_fence(__ATOMIC_RELEASE, "agent");
;       asm volatile("s_waitcnt vmcnt(0)" ::: "memory");
;       const unsigned og = xb_add(&bar[XB_TOP], 1u);
;       const unsigned tg = og / nx;
;       if (og + 1u == (tg + 1u) * nx) xb_add(&bar[XB_TOPGEN], 1u);
;       else XB_SPIN(xb_ld(&bar[XB_TOPGEN]) == tg, bar);
;       __builtin_amdgcn_fence(__ATOMIC_ACQUIRE, "agent");
;       xb_add(&bar[XB_XGEN(x)], 1u);
;       asm volatile("s_waitcnt vmcnt(0)" ::: "memory");
;     } else {
;       XB_SPIN(xb_ld(&bar[XB_XGEN(x)]) == gen, bar);
.LBB0_1568:
	s_lshl_b32 s2, s34, 8
	s_add_u32 s23, s60, s2
	s_addc_u32 s22, s61, 0
	v_mov_b32_e32 v1, s23
	v_add_co_u32_e32 v6, vcc, 0x1000, v1
	v_mov_b32_e32 v1, s22
	s_nop 0
	v_addc_co_u32_e32 v7, vcc, 0, v1, vcc
	flat_atomic_add v3, v[6:7], v225 offset:1024 sc0
	v_cvt_f32_u32_e32 v1, v4
	v_sub_u32_e32 v5, 0, v4
	v_rcp_iflag_f32_e32 v1, v1
	s_nop 0
	v_mul_f32_e32 v1, 0x4f7ffffe, v1
	v_cvt_u32_f32_e32 v1, v1
	v_mul_lo_u32 v5, v5, v1
	v_mul_hi_u32 v5, v1, v5
	v_add_u32_e32 v1, v1, v5
	s_waitcnt vmcnt(0) lgkmcnt(0)
	v_mul_hi_u32 v1, v3, v1
	v_mul_lo_u32 v5, v1, v4
	v_sub_u32_e32 v5, v3, v5
	v_cmp_ge_u32_e32 vcc, v5, v4
	v_add_u32_e32 v6, 1, v1
	v_add_u32_e32 v3, 1, v3
	v_cndmask_b32_e32 v1, v1, v6, vcc
	v_sub_u32_e32 v6, v5, v4
	v_cndmask_b32_e32 v5, v5, v6, vcc
	v_cmp_ge_u32_e32 vcc, v5, v4
	v_add_u32_e32 v5, 1, v1
	s_nop 0
	v_cndmask_b32_e32 v1, v1, v5, vcc
	v_mad_u64_u32 v[4:5], s[2:3], v4, v1, v[4:5]
	v_cmp_ne_u32_e32 vcc, v3, v4
	s_and_saveexec_b64 s[2:3], vcc
	s_xor_b64 s[2:3], exec, s[2:3]
	s_cbranch_execz .LBB0_1581
	s_add_u32 s6, s60, 0x3500
	s_addc_u32 s7, s61, 0
	v_mov_b32_e32 v2, s6
	v_mov_b32_e32 v3, s7
	flat_load_dword v2, v[2:3] sc1
	s_waitcnt vmcnt(0) lgkmcnt(0)
	v_cmp_eq_u32_e32 vcc, v2, v1
	s_and_saveexec_b64 s[4:5], vcc
	s_cbranch_execz .LBB0_1580
	s_mov_b32 s24, 1
	s_mov_b64 s[8:9], 0
	s_branch .LBB0_1572

; template <int DLEN, int LPR, int ROPE, bool KR>
; DI void norm_rows(half_t* base, int stride, int nrows, const float* gain, float oscale, const half_t* zmla, const float2* rtab, int wv_) {
;     ...
;     for (int o = LPR / 2; o > 0; o >>= 1) ss += __shfl_xor(ss, o);
;     const float rstd = rsqrtf(ss * (1.f / DLEN) + EPS);
; #pragma unroll
;     for (int i = 0; i < 8; ++i) f[i] = f[i] * rstd * gn[i];
;     if (ROPE != 0) {
;       constexpr int PX = (ROPE == 64) ? 2 : 1;
;       float pf[8];
; #pragma unroll
;       for (int i = 0; i < 8; ++i) pf[i] = __shfl_xor(f[i], PX);
;       constexpr int RB = (DLEN - ROPE) / 8;
;       if (t < SEQ && s >= RB && active) {
;         const int sr = s - RB;
;         const int q = (ROPE == 64) ? (sr >> 1) : sr;
;         const int pos = (q < 2) ? (t >> 6) : (t & 63);
;         const float sgn = (q & 1) ? 1.f : -1.f;
;         constexpr int NFI = (ROPE == 64) ? 16 : 8;
;         const float2* tb = rtab + ((ROPE == 64) ? 512 : 0) + pos * NFI + ((ROPE == 64) ? (sr & 1) * 8 : 0);
; #pragma unroll
;         for (int i = 0; i < 8; ++i) {
;           const float2 cssn = tb[i];
;           f[i] = f[i] * cssn.x + sgn * pf[i] * cssn.y;
;         }
;       }
;     }
;     if (active) {
;       h8 o;
; #pragma unroll
;       for (int i = 0; i < 8; ++i) o[i] = (half_t)(f[i] * oscale);
;       wt16p(ptr, as_u4(o));
.LBB0_1625:
	s_or_b64 exec, exec, s[2:3]
	s_waitcnt lgkmcnt(0)
	ds_bpermute_b32 v29, v23, v28
	s_waitcnt lgkmcnt(0)
	v_add_f32_e32 v28, v28, v29
	s_waitcnt lgkmcnt(0)
	s_nop 1
	v_add_f32_dpp v28, v28, v28 row_mirror row_mask:0xf bank_mask:0xf
	s_waitcnt lgkmcnt(0)
	s_nop 1
	v_add_f32_dpp v28, v28, v28 row_half_mirror row_mask:0xf bank_mask:0xf
	s_waitcnt lgkmcnt(0)
	s_nop 1
	v_add_f32_dpp v28, v28, v28 quad_perm:[2,3,0,1] row_mask:0xf bank_mask:0xf
	s_and_saveexec_b64 s[8:9], vcc
	s_cbranch_execz .LBB0_1622
	s_waitcnt lgkmcnt(0)
	s_nop 1
	v_add_f32_dpp v28, v28, v28 quad_perm:[1,0,3,2] row_mask:0xf bank_mask:0xf
	v_fmamk_f32 v28, v28, 0x3baaaaab, v222
	v_mul_f32_e32 v29, 0x4b800000, v28
	v_cmp_gt_f32_e64 s[2:3], s73, v28
	s_nop 1
	v_cndmask_b32_e64 v28, v28, v29, s[2:3]
	v_rsq_f32_e32 v28, v28
	s_nop 0
	v_mul_f32_e32 v29, 0x45800000, v28
	v_cndmask_b32_e64 v28, v28, v29, s[2:3]
	v_pk_mul_f32 v[16:17], v[16:17], v[28:29] op_sel_hi:[1,0]
	v_pk_mul_f32 v[20:21], v[20:21], v[28:29] op_sel_hi:[1,0]
	v_pk_mul_f32 v[18:19], v[18:19], v[28:29] op_sel_hi:[1,0]
	v_pk_mul_f32 v[14:15], v[14:15], v[28:29] op_sel_hi:[1,0]
	s_waitcnt vmcnt(0)
	v_pk_mul_f32 v[16:17], v[2:3], v[16:17]
	v_pk_mul_f32 v[20:21], v[4:5], v[20:21]
	v_pk_mul_f32 v[18:19], v[6:7], v[18:19]
	v_pk_mul_f32 v[14:15], v[8:9], v[14:15]
	v_cvt_pk_f16_f32 v16, v16, v17
	v_cvt_pk_f16_f32 v17, v20, v21
	v_cvt_pk_f16_f32 v18, v18, v19
	v_cvt_pk_f16_f32 v19, v14, v15
	global_store_dwordx4 v[12:13], v[16:19], off sc1
	s_nop 1
	s_branch .LBB0_1622

; template <int DLEN, int LPR, int ROPE, bool KR>
; DI void norm_rows(half_t* base, int stride, int nrows, const float* gain, float oscale, const half_t* zmla, const float2* rtab, int wv_) {
;     ...
;   for (int r0 = (blockIdx.x * NWAVE + wave) * RPW; r0 < nrows; r0 += gridDim.x * NWAVE * RPW) {
;     const int rho = r0 + sub;
;     const int t = rho % TOK;
;     half_t* ptr = base + (size_t)rho * stride + s * 8;
;     const half_t* src = ptr;
;     if (KR && s >= 8) {
;       const int b = rho / (4 * TOK);
;       src = zmla + ((size_t)b * TOK + t) * ZS + 128 + (s - 8) * 8;
;     }
;     float f[8];
;     float ss = 0.f;
;     if (active) {
;       const h8 v = *(const h8*)src;
; #pragma unroll
;       for (int i = 0; i < 8; ++i) { f[i] = (float)v[i]; ss += f[i] * f[i]; }
;     } else {
; #pragma unroll
;       for (int i = 0; i < 8; ++i) f[i] = 0.f;
;     }
; #pragma unroll
;     for (int o = LPR / 2; o > 0; o >>= 1) ss += __shfl_xor(ss, o);
;     const float rstd = rsqrtf(ss * (1.f / DLEN) + EPS);
; #pragma unroll
;     for (int i = 0; i < 8; ++i) f[i] = f[i] * rstd * gn[i];
;     if (ROPE != 0) {
;       constexpr int PX = (ROPE == 64) ? 2 : 1;
;       float pf[8];
; #pragma unroll
;       for (int i = 0; i < 8; ++i) pf[i] = __shfl_xor(f[i], PX);
;       constexpr int RB = (DLEN - ROPE) / 8;
;       if (t < SEQ && s >= RB && active) {
;         const int sr = s - RB;
;         const int q = (ROPE == 64) ? (sr >> 1) : sr;
;         const int pos = (q < 2) ? (t >> 6) : (t & 63);
;         const float sgn = (q & 1) ? 1.f : -1.f;
;         constexpr int NFI = (ROPE == 64) ? 16 : 8;
;         const float2* tb = rtab + ((ROPE == 64) ? 512 : 0) + pos * NFI + ((ROPE == 64) ? (sr & 1) * 8 : 0);
; #pragma unroll
;         for (int i = 0; i < 8; ++i) {
;           const float2 cssn = tb[i];
;           f[i] = f[i] * cssn.x + sgn * pf[i] * cssn.y;
;         }
;       }
;     }
;     if (active) {
;       h8 o;
; #pragma unroll
;       for (int i = 0; i < 8; ++i) o[i] = (half_t)(f[i] * oscale);
;       wt16p(ptr, as_u4(o));
;     }
;   }
.LBB0_1629:
	v_add_u32_e32 v17, v12, v1
	v_mad_i64_i32 v[22:23], s[6:7], v17, s9, v[10:11]
	global_load_dwordx4 v[18:21], v[22:23], off
	v_add_u32_e32 v1, s91, v1
	s_waitcnt vmcnt(0)
	v_cvt_f32_f16_e32 v24, v18
	v_cvt_f32_f16_sdwa v25, v18 dst_sel:DWORD dst_unused:UNUSED_PAD src0_sel:WORD_1
	v_cvt_f32_f16_e32 v18, v19
	v_cvt_f32_f16_sdwa v19, v19 dst_sel:DWORD dst_unused:UNUSED_PAD src0_sel:WORD_1
	v_cvt_f32_f16_e32 v26, v20
	v_cvt_f32_f16_sdwa v27, v20 dst_sel:DWORD dst_unused:UNUSED_PAD src0_sel:WORD_1
	v_pk_mul_f32 v[28:29], v[24:25], v[24:25]
	v_cvt_f32_f16_e32 v20, v21
	v_cvt_f32_f16_sdwa v21, v21 dst_sel:DWORD dst_unused:UNUSED_PAD src0_sel:WORD_1
	v_pk_mul_f32 v[30:31], v[18:19], v[18:19]
	v_add_f32_e32 v17, v28, v29
	v_add_f32_e32 v17, v30, v17
	v_pk_mul_f32 v[32:33], v[26:27], v[26:27]
	v_add_f32_e32 v17, v31, v17
	v_add_f32_e32 v17, v32, v17
	v_pk_mul_f32 v[34:35], v[20:21], v[20:21]
	v_add_f32_e32 v17, v33, v17
	v_add_f32_e32 v17, v34, v17
	v_add_f32_e32 v17, v35, v17
	s_waitcnt lgkmcnt(0)
	s_nop 1
	v_add_f32_dpp v17, v17, v17 row_mirror row_mask:0xf bank_mask:0xf
	s_waitcnt lgkmcnt(0)
	s_nop 1
	v_add_f32_dpp v17, v17, v17 row_half_mirror row_mask:0xf bank_mask:0xf
	s_waitcnt lgkmcnt(0)
	s_nop 1
	v_add_f32_dpp v17, v17, v17 quad_perm:[2,3,0,1] row_mask:0xf bank_mask:0xf
	s_waitcnt lgkmcnt(0)
	s_nop 1
	v_add_f32_dpp v17, v17, v17 quad_perm:[1,0,3,2] row_mask:0xf bank_mask:0xf
	v_fmamk_f32 v17, v17, 0x3c000000, v222
	v_mul_f32_e32 v28, 0x4b800000, v17
	v_cmp_gt_f32_e32 vcc, s73, v17
	s_nop 1
	v_cndmask_b32_e32 v17, v17, v28, vcc
	v_rsq_f32_e32 v17, v17
	s_nop 0
	v_mul_f32_e32 v28, 0x45800000, v17
	v_cndmask_b32_e32 v28, v17, v28, vcc
	v_pk_mul_f32 v[24:25], v[28:29], v[24:25] op_sel_hi:[0,1]
	v_pk_mul_f32 v[18:19], v[28:29], v[18:19] op_sel_hi:[0,1]
	v_pk_mul_f32 v[26:27], v[28:29], v[26:27] op_sel_hi:[0,1]
	v_pk_mul_f32 v[20:21], v[28:29], v[20:21] op_sel_hi:[0,1]
	v_pk_mul_f32 v[24:25], v[6:7], v[24:25]
	v_pk_mul_f32 v[28:29], v[8:9], v[18:19]
	v_pk_mul_f32 v[26:27], v[2:3], v[26:27]
	v_pk_mul_f32 v[30:31], v[4:5], v[20:21]
	v_cvt_pk_f16_f32 v18, v24, v25
	v_cvt_pk_f16_f32 v19, v28, v29
	v_cvt_pk_f16_f32 v20, v26, v27
	v_cvt_pk_f16_f32 v21, v30, v31
	global_store_dwordx4 v[22:23], v[18:21], off sc1
	s_nop 1
	v_cmp_lt_i32_e32 vcc, s8, v1
	s_or_b64 s[4:5], vcc, s[4:5]
	s_andn2_b64 exec, exec, s[4:5]
	s_cbranch_execnz .LBB0_1629

; template <int DLEN, int LPR, int ROPE, bool KR>
; DI void norm_rows(half_t* base, int stride, int nrows, const float* gain, float oscale, const half_t* zmla, const float2* rtab, int wv_) {
;     ...
;   for (int r0 = (blockIdx.x * NWAVE + wave) * RPW; r0 < nrows; r0 += gridDim.x * NWAVE * RPW) {
;     const int rho = r0 + sub;
;     const int t = rho % TOK;
;     half_t* ptr = base + (size_t)rho * stride + s * 8;
;     const half_t* src = ptr;
;     if (KR && s >= 8) {
;       const int b = rho / (4 * TOK);
;       src = zmla + ((size_t)b * TOK + t) * ZS + 128 + (s - 8) * 8;
;     }
;     float f[8];
;     float ss = 0.f;
;     if (active) {
;       const h8 v = *(const h8*)src;
; #pragma unroll
;       for (int i = 0; i < 8; ++i) { f[i] = (float)v[i]; ss += f[i] * f[i]; }
;     } else {
; #pragma unroll
;       for (int i = 0; i < 8; ++i) f[i] = 0.f;
;     }
; #pragma unroll
;     for (int o = LPR / 2; o > 0; o >>= 1) ss += __shfl_xor(ss, o);
;     const float rstd = rsqrtf(ss * (1.f / DLEN) + EPS);
; #pragma unroll
;     for (int i = 0; i < 8; ++i) f[i] = f[i] * rstd * gn[i];
;     if (ROPE != 0) {
;       constexpr int PX = (ROPE == 64) ? 2 : 1;
;       float pf[8];
; #pragma unroll
;       for (int i = 0; i < 8; ++i) pf[i] = __shfl_xor(f[i], PX);
;       constexpr int RB = (DLEN - ROPE) / 8;
;       if (t < SEQ && s >= RB && active) {
;         const int sr = s - RB;
;         const int q = (ROPE == 64) ? (sr >> 1) : sr;
;         const int pos = (q < 2) ? (t >> 6) : (t & 63);
;         const float sgn = (q & 1) ? 1.f : -1.f;
;         constexpr int NFI = (ROPE == 64) ? 16 : 8;
;         const float2* tb = rtab + ((ROPE == 64) ? 512 : 0) + pos * NFI + ((ROPE == 64) ? (sr & 1) * 8 : 0);
; #pragma unroll
;         for (int i = 0; i < 8; ++i) {
;           const float2 cssn = tb[i];
;           f[i] = f[i] * cssn.x + sgn * pf[i] * cssn.y;
;         }
;       }
;     }
;     if (active) {
;       h8 o;
; #pragma unroll
;       for (int i = 0; i < 8; ++i) o[i] = (half_t)(f[i] * oscale);
;       wt16p(ptr, as_u4(o));
;     }
;   }
.LBB0_1632:
	v_add_u32_e32 v16, v12, v1
	v_ashrrev_i32_e32 v17, 31, v16
	v_lshlrev_b64 v[16:17], 7, v[16:17]
	v_lshl_add_u64 v[20:21], v[10:11], 0, v[16:17]
	global_load_dwordx4 v[16:19], v[20:21], off
	v_add_u32_e32 v1, s70, v1
	s_waitcnt vmcnt(0)
	v_cvt_f32_f16_e32 v22, v16
	v_cvt_f32_f16_sdwa v23, v16 dst_sel:DWORD dst_unused:UNUSED_PAD src0_sel:WORD_1
	v_cvt_f32_f16_e32 v16, v17
	v_cvt_f32_f16_sdwa v17, v17 dst_sel:DWORD dst_unused:UNUSED_PAD src0_sel:WORD_1
	v_cvt_f32_f16_e32 v24, v18
	v_cvt_f32_f16_sdwa v25, v18 dst_sel:DWORD dst_unused:UNUSED_PAD src0_sel:WORD_1
	v_pk_mul_f32 v[26:27], v[22:23], v[22:23]
	v_cvt_f32_f16_e32 v18, v19
	v_cvt_f32_f16_sdwa v19, v19 dst_sel:DWORD dst_unused:UNUSED_PAD src0_sel:WORD_1
	v_pk_mul_f32 v[28:29], v[16:17], v[16:17]
	v_add_f32_e32 v26, v26, v27
	v_add_f32_e32 v26, v28, v26
	v_pk_mul_f32 v[30:31], v[24:25], v[24:25]
	v_add_f32_e32 v26, v29, v26
	v_add_f32_e32 v26, v30, v26
	v_pk_mul_f32 v[32:33], v[18:19], v[18:19]
	v_add_f32_e32 v26, v31, v26
	v_add_f32_e32 v26, v32, v26
	v_add_f32_e32 v26, v33, v26
	s_waitcnt lgkmcnt(0)
	s_nop 1
	v_add_f32_dpp v26, v26, v26 row_half_mirror row_mask:0xf bank_mask:0xf
	s_waitcnt lgkmcnt(0)
	s_nop 1
	v_add_f32_dpp v26, v26, v26 quad_perm:[2,3,0,1] row_mask:0xf bank_mask:0xf
	s_waitcnt lgkmcnt(0)
	s_nop 1
	v_add_f32_dpp v26, v26, v26 quad_perm:[1,0,3,2] row_mask:0xf bank_mask:0xf
	v_fmamk_f32 v26, v26, 0x3c800000, v222
	v_mul_f32_e32 v27, 0x4b800000, v26
	v_cmp_gt_f32_e32 vcc, s73, v26
	s_nop 1
	v_cndmask_b32_e32 v26, v26, v27, vcc
	v_rsq_f32_e32 v26, v26
	s_nop 0
	v_mul_f32_e32 v27, 0x45800000, v26
	v_cndmask_b32_e32 v26, v26, v27, vcc
	v_pk_mul_f32 v[22:23], v[26:27], v[22:23] op_sel_hi:[0,1]
	v_pk_mul_f32 v[16:17], v[26:27], v[16:17] op_sel_hi:[0,1]
	v_pk_mul_f32 v[24:25], v[26:27], v[24:25] op_sel_hi:[0,1]
	v_pk_mul_f32 v[18:19], v[26:27], v[18:19] op_sel_hi:[0,1]
	v_pk_mul_f32 v[22:23], v[6:7], v[22:23]
	v_pk_mul_f32 v[16:17], v[8:9], v[16:17]
	v_pk_mul_f32 v[24:25], v[2:3], v[24:25]
	v_pk_mul_f32 v[18:19], v[4:5], v[18:19]
	v_pk_mul_f32 v[22:23], v[22:23], s[62:63] op_sel_hi:[1,0]
	v_pk_mul_f32 v[26:27], v[16:17], s[62:63] op_sel_hi:[1,0]
	v_pk_mul_f32 v[24:25], v[24:25], s[62:63] op_sel_hi:[1,0]
	v_pk_mul_f32 v[28:29], v[18:19], s[62:63] op_sel_hi:[1,0]
	v_cvt_pk_f16_f32 v16, v22, v23
	v_cvt_pk_f16_f32 v17, v26, v27
	v_cvt_pk_f16_f32 v18, v24, v25
	v_cvt_pk_f16_f32 v19, v28, v29
	global_store_dwordx4 v[20:21], v[16:19], off sc1
	s_nop 1
	v_cmp_lt_i32_e32 vcc, s93, v1
	s_or_b64 s[4:5], vcc, s[4:5]
	s_andn2_b64 exec, exec, s[4:5]
	s_cbranch_execnz .LBB0_1632

; template <int DLEN, int LPR, int ROPE, bool KR>
; DI void norm_rows(half_t* base, int stride, int nrows, const float* gain, float oscale, const half_t* zmla, const float2* rtab, int wv_) {
;     ...
;   for (int r0 = (blockIdx.x * NWAVE + wave) * RPW; r0 < nrows; r0 += gridDim.x * NWAVE * RPW) {
;     const int rho = r0 + sub;
;     const int t = rho % TOK;
;     half_t* ptr = base + (size_t)rho * stride + s * 8;
;     const half_t* src = ptr;
;     if (KR && s >= 8) {
;       const int b = rho / (4 * TOK);
;       src = zmla + ((size_t)b * TOK + t) * ZS + 128 + (s - 8) * 8;
;     }
;     float f[8];
;     float ss = 0.f;
;     if (active) {
;       const h8 v = *(const h8*)src;
; #pragma unroll
;       for (int i = 0; i < 8; ++i) { f[i] = (float)v[i]; ss += f[i] * f[i]; }
;     } else {
; #pragma unroll
;       for (int i = 0; i < 8; ++i) f[i] = 0.f;
;     }
; #pragma unroll
;     for (int o = LPR / 2; o > 0; o >>= 1) ss += __shfl_xor(ss, o);
;     const float rstd = rsqrtf(ss * (1.f / DLEN) + EPS);
; #pragma unroll
;     for (int i = 0; i < 8; ++i) f[i] = f[i] * rstd * gn[i];
;     if (ROPE != 0) {
;       constexpr int PX = (ROPE == 64) ? 2 : 1;
;       float pf[8];
; #pragma unroll
;       for (int i = 0; i < 8; ++i) pf[i] = __shfl_xor(f[i], PX);
;       constexpr int RB = (DLEN - ROPE) / 8;
;       if (t < SEQ && s >= RB && active) {
;         const int sr = s - RB;
;         const int q = (ROPE == 64) ? (sr >> 1) : sr;
;         const int pos = (q < 2) ? (t >> 6) : (t & 63);
;         const float sgn = (q & 1) ? 1.f : -1.f;
;         constexpr int NFI = (ROPE == 64) ? 16 : 8;
;         const float2* tb = rtab + ((ROPE == 64) ? 512 : 0) + pos * NFI + ((ROPE == 64) ? (sr & 1) * 8 : 0);
; #pragma unroll
;         for (int i = 0; i < 8; ++i) {
;           const float2 cssn = tb[i];
;           f[i] = f[i] * cssn.x + sgn * pf[i] * cssn.y;
;         }
;       }
;     }
;     if (active) {
;       h8 o;
; #pragma unroll
;       for (int i = 0; i < 8; ++i) o[i] = (half_t)(f[i] * oscale);
;       wt16p(ptr, as_u4(o));
;     }
;   }
.LBB0_1635:
	v_add_u32_e32 v16, v12, v1
	v_ashrrev_i32_e32 v17, 31, v16
	v_lshlrev_b64 v[16:17], 7, v[16:17]
	v_lshl_add_u64 v[20:21], v[10:11], 0, v[16:17]
	global_load_dwordx4 v[16:19], v[20:21], off
	v_add_u32_e32 v1, s70, v1
	s_waitcnt vmcnt(0)
	v_cvt_f32_f16_e32 v22, v16
	v_cvt_f32_f16_sdwa v23, v16 dst_sel:DWORD dst_unused:UNUSED_PAD src0_sel:WORD_1
	v_cvt_f32_f16_e32 v16, v17
	v_cvt_f32_f16_sdwa v17, v17 dst_sel:DWORD dst_unused:UNUSED_PAD src0_sel:WORD_1
	v_cvt_f32_f16_e32 v24, v18
	v_cvt_f32_f16_sdwa v25, v18 dst_sel:DWORD dst_unused:UNUSED_PAD src0_sel:WORD_1
	v_pk_mul_f32 v[26:27], v[22:23], v[22:23]
	v_cvt_f32_f16_e32 v18, v19
	v_cvt_f32_f16_sdwa v19, v19 dst_sel:DWORD dst_unused:UNUSED_PAD src0_sel:WORD_1
	v_pk_mul_f32 v[28:29], v[16:17], v[16:17]
	v_add_f32_e32 v26, v26, v27
	v_add_f32_e32 v26, v28, v26
	v_pk_mul_f32 v[30:31], v[24:25], v[24:25]
	v_add_f32_e32 v26, v29, v26
	v_add_f32_e32 v26, v30, v26
	v_pk_mul_f32 v[32:33], v[18:19], v[18:19]
	v_add_f32_e32 v26, v31, v26
	v_add_f32_e32 v26, v32, v26
	v_add_f32_e32 v26, v33, v26
	s_waitcnt lgkmcnt(0)
	s_nop 1
	v_add_f32_dpp v26, v26, v26 row_half_mirror row_mask:0xf bank_mask:0xf
	s_waitcnt lgkmcnt(0)
	s_nop 1
	v_add_f32_dpp v26, v26, v26 quad_perm:[2,3,0,1] row_mask:0xf bank_mask:0xf
	s_waitcnt lgkmcnt(0)
	s_nop 1
	v_add_f32_dpp v26, v26, v26 quad_perm:[1,0,3,2] row_mask:0xf bank_mask:0xf
	v_fmamk_f32 v26, v26, 0x3c800000, v222
	v_mul_f32_e32 v27, 0x4b800000, v26
	v_cmp_gt_f32_e32 vcc, s73, v26
	s_nop 1
	v_cndmask_b32_e32 v26, v26, v27, vcc
	v_rsq_f32_e32 v26, v26
	s_nop 0
	v_mul_f32_e32 v27, 0x45800000, v26
	v_cndmask_b32_e32 v26, v26, v27, vcc
	v_pk_mul_f32 v[22:23], v[26:27], v[22:23] op_sel_hi:[0,1]
	v_pk_mul_f32 v[16:17], v[26:27], v[16:17] op_sel_hi:[0,1]
	v_pk_mul_f32 v[24:25], v[26:27], v[24:25] op_sel_hi:[0,1]
	v_pk_mul_f32 v[18:19], v[26:27], v[18:19] op_sel_hi:[0,1]
	v_pk_mul_f32 v[22:23], v[6:7], v[22:23]
	v_pk_mul_f32 v[26:27], v[8:9], v[16:17]
	v_pk_mul_f32 v[24:25], v[2:3], v[24:25]
	v_pk_mul_f32 v[28:29], v[4:5], v[18:19]
	v_cvt_pk_f16_f32 v16, v22, v23
	v_cvt_pk_f16_f32 v17, v26, v27
	v_cvt_pk_f16_f32 v18, v24, v25
	v_cvt_pk_f16_f32 v19, v28, v29
	global_store_dwordx4 v[20:21], v[16:19], off sc1
	s_nop 1
	v_cmp_lt_i32_e32 vcc, s93, v1
	s_or_b64 s[4:5], vcc, s[4:5]
	s_andn2_b64 exec, exec, s[4:5]
	s_cbranch_execnz .LBB0_1635

; template <int DLEN, int LPR, int ROPE, bool KR>
; DI void norm_rows(half_t* base, int stride, int nrows, const float* gain, float oscale, const half_t* zmla, const float2* rtab, int wv_) {
;     ...
;   for (int r0 = (blockIdx.x * NWAVE + wave) * RPW; r0 < nrows; r0 += gridDim.x * NWAVE * RPW) {
;     const int rho = r0 + sub;
;     const int t = rho % TOK;
;     half_t* ptr = base + (size_t)rho * stride + s * 8;
;     const half_t* src = ptr;
;     if (KR && s >= 8) {
;       const int b = rho / (4 * TOK);
;       src = zmla + ((size_t)b * TOK + t) * ZS + 128 + (s - 8) * 8;
;     }
;     float f[8];
;     float ss = 0.f;
;     if (active) {
;       const h8 v = *(const h8*)src;
; #pragma unroll
;       for (int i = 0; i < 8; ++i) { f[i] = (float)v[i]; ss += f[i] * f[i]; }
;     } else {
; #pragma unroll
;       for (int i = 0; i < 8; ++i) f[i] = 0.f;
;     }
; #pragma unroll
;     for (int o = LPR / 2; o > 0; o >>= 1) ss += __shfl_xor(ss, o);
;     const float rstd = rsqrtf(ss * (1.f / DLEN) + EPS);
; #pragma unroll
;     for (int i = 0; i < 8; ++i) f[i] = f[i] * rstd * gn[i];
;     if (ROPE != 0) {
;       constexpr int PX = (ROPE == 64) ? 2 : 1;
;       float pf[8];
; #pragma unroll
;       for (int i = 0; i < 8; ++i) pf[i] = __shfl_xor(f[i], PX);
;       constexpr int RB = (DLEN - ROPE) / 8;
;       if (t < SEQ && s >= RB && active) {
;         const int sr = s - RB;
;         const int q = (ROPE == 64) ? (sr >> 1) : sr;
;         const int pos = (q < 2) ? (t >> 6) : (t & 63);
;         const float sgn = (q & 1) ? 1.f : -1.f;
;         constexpr int NFI = (ROPE == 64) ? 16 : 8;
;         const float2* tb = rtab + ((ROPE == 64) ? 512 : 0) + pos * NFI + ((ROPE == 64) ? (sr & 1) * 8 : 0);
; #pragma unroll
;         for (int i = 0; i < 8; ++i) {
;           const float2 cssn = tb[i];
;           f[i] = f[i] * cssn.x + sgn * pf[i] * cssn.y;
;         }
;       }
;     }
.LBB0_1639:
	v_add_u32_e32 v34, v22, v1
	v_ashrrev_i32_e32 v35, 31, v34
	v_lshlrev_b64 v[12:13], 6, v[34:35]
	v_lshl_add_u64 v[12:13], v[10:11], 0, v[12:13]
	global_load_dwordx4 v[14:17], v[12:13], off
	s_waitcnt vmcnt(0)
	v_cvt_f32_f16_e32 v20, v14
	v_cvt_f32_f16_sdwa v21, v14 dst_sel:DWORD dst_unused:UNUSED_PAD src0_sel:WORD_1
	v_cvt_f32_f16_e32 v14, v15
	v_cvt_f32_f16_sdwa v15, v15 dst_sel:DWORD dst_unused:UNUSED_PAD src0_sel:WORD_1
	v_cvt_f32_f16_e32 v26, v16
	v_cvt_f32_f16_sdwa v27, v16 dst_sel:DWORD dst_unused:UNUSED_PAD src0_sel:WORD_1
	v_pk_mul_f32 v[28:29], v[20:21], v[20:21]
	v_cvt_f32_f16_e32 v18, v17
	v_cvt_f32_f16_sdwa v19, v17 dst_sel:DWORD dst_unused:UNUSED_PAD src0_sel:WORD_1
	v_pk_mul_f32 v[30:31], v[14:15], v[14:15]
	v_add_f32_e32 v25, v28, v29
	v_add_f32_e32 v25, v30, v25
	v_pk_mul_f32 v[32:33], v[26:27], v[26:27]
	v_add_f32_e32 v25, v31, v25
	v_add_f32_e32 v25, v32, v25
	v_pk_mul_f32 v[16:17], v[18:19], v[18:19]
	v_add_f32_e32 v25, v33, v25
	v_add_f32_e32 v16, v16, v25
	v_add_f32_e32 v16, v17, v16
	v_mul_hi_i32 v33, v34, s71
	v_lshrrev_b32_e32 v35, 31, v33
	v_ashrrev_i32_e32 v33, 9, v33
	v_add_u32_e32 v33, v33, v35
	s_waitcnt lgkmcnt(0)
	s_nop 1
	v_add_f32_dpp v16, v16, v16 quad_perm:[2,3,0,1] row_mask:0xf bank_mask:0xf
	v_mul_i32_i24_e32 v33, 0x900, v33
	v_sub_u32_e32 v33, v34, v33
	s_waitcnt lgkmcnt(0)
	s_nop 1
	v_add_f32_dpp v16, v16, v16 quad_perm:[1,0,3,2] row_mask:0xf bank_mask:0xf
	v_fmamk_f32 v16, v16, 0x3d000000, v222
	v_mul_f32_e32 v17, 0x4b800000, v16
	v_cmp_gt_f32_e64 s[4:5], s73, v16
	s_nop 1
	v_cndmask_b32_e64 v16, v16, v17, s[4:5]
	v_rsq_f32_e32 v16, v16
	s_nop 0
	v_mul_f32_e32 v17, 0x45800000, v16
	v_cndmask_b32_e64 v16, v16, v17, s[4:5]
	v_pk_mul_f32 v[20:21], v[16:17], v[20:21] op_sel_hi:[0,1]
	v_pk_mul_f32 v[14:15], v[16:17], v[14:15] op_sel_hi:[0,1]
	v_pk_mul_f32 v[26:27], v[16:17], v[26:27] op_sel_hi:[0,1]
	v_pk_mul_f32 v[28:29], v[16:17], v[18:19] op_sel_hi:[0,1]
	v_pk_mul_f32 v[20:21], v[6:7], v[20:21]
	v_pk_mul_f32 v[18:19], v[8:9], v[14:15]
	v_pk_mul_f32 v[16:17], v[2:3], v[26:27]
	v_pk_mul_f32 v[14:15], v[4:5], v[28:29]
	s_nop 1
	v_mov_b32_dpp v31, v20 quad_perm:[1,0,3,2] row_mask:0xf bank_mask:0xf
	v_mov_b32_dpp v32, v21 quad_perm:[1,0,3,2] row_mask:0xf bank_mask:0xf
	v_mov_b32_dpp v29, v18 quad_perm:[1,0,3,2] row_mask:0xf bank_mask:0xf
	v_mov_b32_dpp v30, v19 quad_perm:[1,0,3,2] row_mask:0xf bank_mask:0xf
	v_mov_b32_dpp v27, v16 quad_perm:[1,0,3,2] row_mask:0xf bank_mask:0xf
	v_mov_b32_dpp v28, v17 quad_perm:[1,0,3,2] row_mask:0xf bank_mask:0xf
	v_mov_b32_dpp v26, v14 quad_perm:[1,0,3,2] row_mask:0xf bank_mask:0xf
	v_mov_b32_dpp v25, v15 quad_perm:[1,0,3,2] row_mask:0xf bank_mask:0xf
	v_cmp_gt_i32_e64 s[4:5], s85, v33
	s_and_saveexec_b64 s[10:11], s[4:5]
	s_cbranch_execz .LBB0_1638
	v_lshrrev_b32_e32 v34, 6, v33
	v_and_b32_e32 v33, 63, v33
	v_cndmask_b32_e32 v33, v33, v34, vcc
	v_lshlrev_b32_e32 v33, 6, v33
	ds_read_b128 v[34:37], v33
	ds_read_b128 v[38:41], v33 offset:16
	ds_read_b128 v[42:45], v33 offset:32
	ds_read_b128 v[46:49], v33 offset:48
	s_waitcnt lgkmcnt(11)
	v_cndmask_b32_e64 v52, v31, -v31, s[2:3]
	s_waitcnt lgkmcnt(10)
	v_cndmask_b32_e64 v31, v32, -v32, s[2:3]
	s_waitcnt lgkmcnt(3)
	v_mov_b32_e32 v50, v35
	v_mov_b32_e32 v53, v21
	v_mov_b32_e32 v21, v31
	v_mov_b32_e32 v35, v37
	v_pk_mul_f32 v[20:21], v[20:21], v[34:35]
	v_cndmask_b32_e64 v34, v29, -v29, s[2:3]
	v_cndmask_b32_e64 v29, v30, -v30, s[2:3]
	v_mov_b32_e32 v51, v36
	v_mov_b32_e32 v35, v19
	v_mov_b32_e32 v19, v29
	v_cndmask_b32_e64 v36, v27, -v27, s[2:3]
	v_cndmask_b32_e64 v27, v28, -v28, s[2:3]
	v_cndmask_b32_e64 v29, v25, -v25, s[2:3]
	v_mov_b32_e32 v28, v15
	s_waitcnt lgkmcnt(2)
	v_mov_b32_e32 v32, v39
	v_mov_b32_e32 v39, v41
	s_waitcnt lgkmcnt(1)
	v_mov_b32_e32 v30, v43
	v_mov_b32_e32 v37, v17
	v_mov_b32_e32 v17, v27
	v_mov_b32_e32 v43, v45
	v_cndmask_b32_e64 v26, v26, -v26, s[2:3]
	s_waitcnt lgkmcnt(0)
	v_pk_mul_f32 v[28:29], v[28:29], v[48:49]
	v_mov_b32_e32 v33, v40
	v_pk_mul_f32 v[18:19], v[18:19], v[38:39]
	v_mov_b32_e32 v31, v44
	v_pk_mul_f32 v[16:17], v[16:17], v[42:43]
	v_mul_f32_e32 v14, v14, v46
	v_mul_f32_e32 v26, v26, v47
	v_mov_b32_e32 v15, v28
	v_mov_b32_e32 v27, v29
	v_pk_fma_f32 v[20:21], v[52:53], v[50:51], v[20:21]
	v_pk_fma_f32 v[18:19], v[34:35], v[32:33], v[18:19]
	v_pk_fma_f32 v[16:17], v[36:37], v[30:31], v[16:17]
	v_pk_add_f32 v[14:15], v[14:15], v[26:27]
	s_branch .LBB0_1638

; template <int DLEN, int LPR, int ROPE, bool KR>
; DI void norm_rows(half_t* base, int stride, int nrows, const float* gain, float oscale, const half_t* zmla, const float2* rtab, int wv_) {
;     ...
;   for (int r0 = (blockIdx.x * NWAVE + wave) * RPW; r0 < nrows; r0 += gridDim.x * NWAVE * RPW) {
;     const int rho = r0 + sub;
;     const int t = rho % TOK;
;     half_t* ptr = base + (size_t)rho * stride + s * 8;
;     const half_t* src = ptr;
;     if (KR && s >= 8) {
;       const int b = rho / (4 * TOK);
;       src = zmla + ((size_t)b * TOK + t) * ZS + 128 + (s - 8) * 8;
;     }
;     float f[8];
;     float ss = 0.f;
;     if (active) {
;       const h8 v = *(const h8*)src;
; #pragma unroll
;       for (int i = 0; i < 8; ++i) { f[i] = (float)v[i]; ss += f[i] * f[i]; }
;     } else {
; #pragma unroll
;       for (int i = 0; i < 8; ++i) f[i] = 0.f;
;     }
; #pragma unroll
;     for (int o = LPR / 2; o > 0; o >>= 1) ss += __shfl_xor(ss, o);
;     const float rstd = rsqrtf(ss * (1.f / DLEN) + EPS);
; #pragma unroll
;     for (int i = 0; i < 8; ++i) f[i] = f[i] * rstd * gn[i];
;     if (ROPE != 0) {
;       constexpr int PX = (ROPE == 64) ? 2 : 1;
;       float pf[8];
; #pragma unroll
;       for (int i = 0; i < 8; ++i) pf[i] = __shfl_xor(f[i], PX);
;       constexpr int RB = (DLEN - ROPE) / 8;
;       if (t < SEQ && s >= RB && active) {
;         const int sr = s - RB;
;         const int q = (ROPE == 64) ? (sr >> 1) : sr;
;         const int pos = (q < 2) ? (t >> 6) : (t & 63);
;         const float sgn = (q & 1) ? 1.f : -1.f;
;         constexpr int NFI = (ROPE == 64) ? 16 : 8;
;         const float2* tb = rtab + ((ROPE == 64) ? 512 : 0) + pos * NFI + ((ROPE == 64) ? (sr & 1) * 8 : 0);
; #pragma unroll
;         for (int i = 0; i < 8; ++i) {
;           const float2 cssn = tb[i];
;           f[i] = f[i] * cssn.x + sgn * pf[i] * cssn.y;
;         }
;       }
;     }
.LBB0_1644:
	v_add_u32_e32 v34, v22, v1
	v_ashrrev_i32_e32 v35, 31, v34
	v_lshlrev_b64 v[12:13], 6, v[34:35]
	v_lshl_add_u64 v[12:13], v[10:11], 0, v[12:13]
	global_load_dwordx4 v[14:17], v[12:13], off
	s_waitcnt vmcnt(0)
	v_cvt_f32_f16_e32 v20, v14
	v_cvt_f32_f16_sdwa v21, v14 dst_sel:DWORD dst_unused:UNUSED_PAD src0_sel:WORD_1
	v_cvt_f32_f16_e32 v14, v15
	v_cvt_f32_f16_sdwa v15, v15 dst_sel:DWORD dst_unused:UNUSED_PAD src0_sel:WORD_1
	v_cvt_f32_f16_e32 v26, v16
	v_cvt_f32_f16_sdwa v27, v16 dst_sel:DWORD dst_unused:UNUSED_PAD src0_sel:WORD_1
	v_pk_mul_f32 v[28:29], v[20:21], v[20:21]
	v_cvt_f32_f16_e32 v18, v17
	v_cvt_f32_f16_sdwa v19, v17 dst_sel:DWORD dst_unused:UNUSED_PAD src0_sel:WORD_1
	v_pk_mul_f32 v[30:31], v[14:15], v[14:15]
	s_waitcnt lgkmcnt(0)
	v_add_f32_e32 v25, v28, v29
	v_add_f32_e32 v25, v30, v25
	v_pk_mul_f32 v[32:33], v[26:27], v[26:27]
	v_add_f32_e32 v25, v31, v25
	v_add_f32_e32 v25, v32, v25
	v_pk_mul_f32 v[16:17], v[18:19], v[18:19]
	v_add_f32_e32 v25, v33, v25
	v_add_f32_e32 v16, v16, v25
	v_add_f32_e32 v16, v17, v16
	v_mul_hi_i32 v33, v34, s71
	v_lshrrev_b32_e32 v35, 31, v33
	v_ashrrev_i32_e32 v33, 9, v33
	v_add_u32_e32 v33, v33, v35
	s_waitcnt lgkmcnt(0)
	s_nop 1
	v_add_f32_dpp v16, v16, v16 quad_perm:[2,3,0,1] row_mask:0xf bank_mask:0xf
	v_mul_i32_i24_e32 v33, 0x900, v33
	v_sub_u32_e32 v33, v34, v33
	s_waitcnt lgkmcnt(0)
	s_nop 1
	v_add_f32_dpp v16, v16, v16 quad_perm:[1,0,3,2] row_mask:0xf bank_mask:0xf
	v_fmamk_f32 v16, v16, 0x3d000000, v222
	v_mul_f32_e32 v17, 0x4b800000, v16
	v_cmp_gt_f32_e64 s[4:5], s73, v16
	s_nop 1
	v_cndmask_b32_e64 v16, v16, v17, s[4:5]
	v_rsq_f32_e32 v16, v16
	s_nop 0
	v_mul_f32_e32 v17, 0x45800000, v16
	v_cndmask_b32_e64 v16, v16, v17, s[4:5]
	v_pk_mul_f32 v[20:21], v[16:17], v[20:21] op_sel_hi:[0,1]
	v_pk_mul_f32 v[14:15], v[16:17], v[14:15] op_sel_hi:[0,1]
	v_pk_mul_f32 v[26:27], v[16:17], v[26:27] op_sel_hi:[0,1]
	v_pk_mul_f32 v[28:29], v[16:17], v[18:19] op_sel_hi:[0,1]
	v_pk_mul_f32 v[20:21], v[6:7], v[20:21]
	v_pk_mul_f32 v[18:19], v[8:9], v[14:15]
	v_pk_mul_f32 v[16:17], v[2:3], v[26:27]
	v_pk_mul_f32 v[14:15], v[4:5], v[28:29]
	s_nop 1
	v_mov_b32_dpp v31, v20 quad_perm:[1,0,3,2] row_mask:0xf bank_mask:0xf
	v_mov_b32_dpp v32, v21 quad_perm:[1,0,3,2] row_mask:0xf bank_mask:0xf
	v_mov_b32_dpp v29, v18 quad_perm:[1,0,3,2] row_mask:0xf bank_mask:0xf
	v_mov_b32_dpp v30, v19 quad_perm:[1,0,3,2] row_mask:0xf bank_mask:0xf
	v_mov_b32_dpp v27, v16 quad_perm:[1,0,3,2] row_mask:0xf bank_mask:0xf
	v_mov_b32_dpp v28, v17 quad_perm:[1,0,3,2] row_mask:0xf bank_mask:0xf
	v_mov_b32_dpp v26, v14 quad_perm:[1,0,3,2] row_mask:0xf bank_mask:0xf
	v_mov_b32_dpp v25, v15 quad_perm:[1,0,3,2] row_mask:0xf bank_mask:0xf
	v_cmp_gt_i32_e64 s[4:5], s85, v33
	s_and_saveexec_b64 s[10:11], s[4:5]
	s_cbranch_execz .LBB0_1643
	v_lshrrev_b32_e32 v34, 6, v33
	v_and_b32_e32 v33, 63, v33
	v_cndmask_b32_e32 v33, v33, v34, vcc
	v_lshlrev_b32_e32 v33, 6, v33
	ds_read_b128 v[34:37], v33
	ds_read_b128 v[38:41], v33 offset:16
	ds_read_b128 v[42:45], v33 offset:32
	ds_read_b128 v[46:49], v33 offset:48
	s_waitcnt lgkmcnt(11)
	v_cndmask_b32_e64 v52, v31, -v31, s[2:3]
	s_waitcnt lgkmcnt(10)
	v_cndmask_b32_e64 v31, v32, -v32, s[2:3]
	s_waitcnt lgkmcnt(3)
	v_mov_b32_e32 v50, v35
	v_mov_b32_e32 v53, v21
	v_mov_b32_e32 v21, v31
	v_mov_b32_e32 v35, v37
	v_pk_mul_f32 v[20:21], v[20:21], v[34:35]
	v_cndmask_b32_e64 v34, v29, -v29, s[2:3]
	v_cndmask_b32_e64 v29, v30, -v30, s[2:3]
	v_mov_b32_e32 v51, v36
	v_mov_b32_e32 v35, v19
	v_mov_b32_e32 v19, v29
	v_cndmask_b32_e64 v36, v27, -v27, s[2:3]
	v_cndmask_b32_e64 v27, v28, -v28, s[2:3]
	v_cndmask_b32_e64 v29, v25, -v25, s[2:3]
	v_mov_b32_e32 v28, v15
	s_waitcnt lgkmcnt(2)
	v_mov_b32_e32 v32, v39
	v_mov_b32_e32 v39, v41
	s_waitcnt lgkmcnt(1)
	v_mov_b32_e32 v30, v43
	v_mov_b32_e32 v37, v17
	v_mov_b32_e32 v17, v27
	v_mov_b32_e32 v43, v45
	v_cndmask_b32_e64 v26, v26, -v26, s[2:3]
	s_waitcnt lgkmcnt(0)
	v_pk_mul_f32 v[28:29], v[28:29], v[48:49]
	v_mov_b32_e32 v33, v40
	v_pk_mul_f32 v[18:19], v[18:19], v[38:39]
	v_mov_b32_e32 v31, v44
	v_pk_mul_f32 v[16:17], v[16:17], v[42:43]
	v_mul_f32_e32 v14, v14, v46
	v_mul_f32_e32 v26, v26, v47
	v_mov_b32_e32 v15, v28
	v_mov_b32_e32 v27, v29
	v_pk_fma_f32 v[20:21], v[52:53], v[50:51], v[20:21]
	v_pk_fma_f32 v[18:19], v[34:35], v[32:33], v[18:19]
	v_pk_fma_f32 v[16:17], v[36:37], v[30:31], v[16:17]
	v_pk_add_f32 v[14:15], v[14:15], v[26:27]
	s_branch .LBB0_1643

; template <int DLEN, int LPR, int ROPE, bool KR>
; DI void norm_rows(half_t* base, int stride, int nrows, const float* gain, float oscale, const half_t* zmla, const float2* rtab, int wv_) {
;     ...
;   for (int r0 = (blockIdx.x * NWAVE + wave) * RPW; r0 < nrows; r0 += gridDim.x * NWAVE * RPW) {
;     const int rho = r0 + sub;
;     const int t = rho % TOK;
;     half_t* ptr = base + (size_t)rho * stride + s * 8;
;     const half_t* src = ptr;
;     if (KR && s >= 8) {
;       const int b = rho / (4 * TOK);
;       src = zmla + ((size_t)b * TOK + t) * ZS + 128 + (s - 8) * 8;
;     }
;     float f[8];
;     float ss = 0.f;
;     if (active) {
;       const h8 v = *(const h8*)src;
; #pragma unroll
;       for (int i = 0; i < 8; ++i) { f[i] = (float)v[i]; ss += f[i] * f[i]; }
;     } else {
; #pragma unroll
;       for (int i = 0; i < 8; ++i) f[i] = 0.f;
;     }
; #pragma unroll
;     for (int o = LPR / 2; o > 0; o >>= 1) ss += __shfl_xor(ss, o);
;     const float rstd = rsqrtf(ss * (1.f / DLEN) + EPS);
; #pragma unroll
;     for (int i = 0; i < 8; ++i) f[i] = f[i] * rstd * gn[i];
;     if (ROPE != 0) {
;       constexpr int PX = (ROPE == 64) ? 2 : 1;
;       float pf[8];
; #pragma unroll
;       for (int i = 0; i < 8; ++i) pf[i] = __shfl_xor(f[i], PX);
;       constexpr int RB = (DLEN - ROPE) / 8;
;       if (t < SEQ && s >= RB && active) {
;         const int sr = s - RB;
;         const int q = (ROPE == 64) ? (sr >> 1) : sr;
;         const int pos = (q < 2) ? (t >> 6) : (t & 63);
;         const float sgn = (q & 1) ? 1.f : -1.f;
;         constexpr int NFI = (ROPE == 64) ? 16 : 8;
;         const float2* tb = rtab + ((ROPE == 64) ? 512 : 0) + pos * NFI + ((ROPE == 64) ? (sr & 1) * 8 : 0);
; #pragma unroll
;         for (int i = 0; i < 8; ++i) {
;           const float2 cssn = tb[i];
;           f[i] = f[i] * cssn.x + sgn * pf[i] * cssn.y;
;         }
;       }
;     }
.LBB0_1649:
	v_add_u32_e32 v36, v22, v1
	v_ashrrev_i32_e32 v37, 31, v36
	v_lshlrev_b64 v[12:13], 7, v[36:37]
	v_lshl_add_u64 v[12:13], v[10:11], 0, v[12:13]
	global_load_dwordx4 v[14:17], v[12:13], off
	s_waitcnt vmcnt(0)
	v_cvt_f32_f16_e32 v18, v14
	v_cvt_f32_f16_sdwa v19, v14 dst_sel:DWORD dst_unused:UNUSED_PAD src0_sel:WORD_1
	v_cvt_f32_f16_e32 v14, v15
	v_cvt_f32_f16_sdwa v15, v15 dst_sel:DWORD dst_unused:UNUSED_PAD src0_sel:WORD_1
	v_cvt_f32_f16_e32 v20, v16
	v_cvt_f32_f16_sdwa v21, v16 dst_sel:DWORD dst_unused:UNUSED_PAD src0_sel:WORD_1
	v_pk_mul_f32 v[28:29], v[18:19], v[18:19]
	v_cvt_f32_f16_e32 v16, v17
	v_cvt_f32_f16_sdwa v17, v17 dst_sel:DWORD dst_unused:UNUSED_PAD src0_sel:WORD_1
	v_pk_mul_f32 v[30:31], v[14:15], v[14:15]
	v_add_f32_e32 v27, v28, v29
	v_add_f32_e32 v27, v30, v27
	v_pk_mul_f32 v[32:33], v[20:21], v[20:21]
	v_add_f32_e32 v27, v31, v27
	v_add_f32_e32 v27, v32, v27
	v_pk_mul_f32 v[34:35], v[16:17], v[16:17]
	v_add_f32_e32 v27, v33, v27
	v_add_f32_e32 v27, v34, v27
	v_add_f32_e32 v27, v35, v27
	v_mul_hi_i32 v35, v36, s71
	v_lshrrev_b32_e32 v37, 31, v35
	v_ashrrev_i32_e32 v35, 9, v35
	v_add_u32_e32 v35, v35, v37
	s_waitcnt lgkmcnt(0)
	s_nop 1
	v_add_f32_dpp v27, v27, v27 row_half_mirror row_mask:0xf bank_mask:0xf
	v_mul_i32_i24_e32 v35, 0x900, v35
	v_sub_u32_e32 v35, v36, v35
	s_waitcnt lgkmcnt(0)
	s_nop 1
	v_add_f32_dpp v27, v27, v27 quad_perm:[2,3,0,1] row_mask:0xf bank_mask:0xf
	s_waitcnt lgkmcnt(0)
	s_nop 1
	v_add_f32_dpp v27, v27, v27 quad_perm:[1,0,3,2] row_mask:0xf bank_mask:0xf
	v_fmamk_f32 v27, v27, 0x3c800000, v222
	v_mul_f32_e32 v28, 0x4b800000, v27
	v_cmp_gt_f32_e64 s[4:5], s73, v27
	s_nop 1
	v_cndmask_b32_e64 v27, v27, v28, s[4:5]
	v_rsq_f32_e32 v27, v27
	s_nop 0
	v_mul_f32_e32 v28, 0x45800000, v27
	v_cndmask_b32_e64 v28, v27, v28, s[4:5]
	v_pk_mul_f32 v[18:19], v[28:29], v[18:19] op_sel_hi:[0,1]
	v_pk_mul_f32 v[14:15], v[28:29], v[14:15] op_sel_hi:[0,1]
	v_pk_mul_f32 v[30:31], v[28:29], v[20:21] op_sel_hi:[0,1]
	v_pk_mul_f32 v[28:29], v[28:29], v[16:17] op_sel_hi:[0,1]
	v_pk_mul_f32 v[20:21], v[6:7], v[18:19]
	v_pk_mul_f32 v[18:19], v[8:9], v[14:15]
	v_pk_mul_f32 v[16:17], v[2:3], v[30:31]
	v_pk_mul_f32 v[14:15], v[4:5], v[28:29]
	s_nop 1
	v_mov_b32_dpp v33, v20 quad_perm:[2,3,0,1] row_mask:0xf bank_mask:0xf
	v_mov_b32_dpp v34, v21 quad_perm:[2,3,0,1] row_mask:0xf bank_mask:0xf
	v_mov_b32_dpp v31, v18 quad_perm:[2,3,0,1] row_mask:0xf bank_mask:0xf
	v_mov_b32_dpp v32, v19 quad_perm:[2,3,0,1] row_mask:0xf bank_mask:0xf
	v_mov_b32_dpp v29, v16 quad_perm:[2,3,0,1] row_mask:0xf bank_mask:0xf
	v_mov_b32_dpp v30, v17 quad_perm:[2,3,0,1] row_mask:0xf bank_mask:0xf
	v_mov_b32_dpp v28, v14 quad_perm:[2,3,0,1] row_mask:0xf bank_mask:0xf
	v_mov_b32_dpp v27, v15 quad_perm:[2,3,0,1] row_mask:0xf bank_mask:0xf
	v_cmp_gt_i32_e64 s[4:5], s85, v35
	s_and_saveexec_b64 s[10:11], s[4:5]
	s_cbranch_execz .LBB0_1648
	v_lshrrev_b32_e32 v36, 6, v35
	v_and_b32_e32 v35, 63, v35
	v_cndmask_b32_e32 v35, v35, v36, vcc
	v_lshl_or_b32 v35, v35, 7, v24
	ds_read_b128 v[36:39], v35 offset:4096
	ds_read_b128 v[40:43], v35 offset:4112
	ds_read_b128 v[44:47], v35 offset:4128
	ds_read_b128 v[48:51], v35 offset:4144
	s_waitcnt lgkmcnt(11)
	v_cndmask_b32_e64 v54, v33, -v33, s[2:3]
	s_waitcnt lgkmcnt(10)
	v_cndmask_b32_e64 v33, v34, -v34, s[2:3]
	s_waitcnt lgkmcnt(3)
	v_mov_b32_e32 v52, v37
	v_mov_b32_e32 v55, v21
	v_mov_b32_e32 v21, v33
	v_mov_b32_e32 v37, v39
	v_pk_mul_f32 v[20:21], v[20:21], v[36:37]
	v_cndmask_b32_e64 v36, v31, -v31, s[2:3]
	v_cndmask_b32_e64 v31, v32, -v32, s[2:3]
	v_mov_b32_e32 v53, v38
	v_mov_b32_e32 v37, v19
	v_mov_b32_e32 v19, v31
	v_cndmask_b32_e64 v38, v29, -v29, s[2:3]
	v_cndmask_b32_e64 v29, v30, -v30, s[2:3]
	v_cndmask_b32_e64 v31, v27, -v27, s[2:3]
	v_mov_b32_e32 v30, v15
	s_waitcnt lgkmcnt(2)
	v_mov_b32_e32 v34, v41
	v_mov_b32_e32 v41, v43
	s_waitcnt lgkmcnt(1)
	v_mov_b32_e32 v32, v45
	v_mov_b32_e32 v39, v17
	v_mov_b32_e32 v17, v29
	v_mov_b32_e32 v45, v47
	v_cndmask_b32_e64 v28, v28, -v28, s[2:3]
	s_waitcnt lgkmcnt(0)
	v_pk_mul_f32 v[30:31], v[30:31], v[50:51]
	v_mov_b32_e32 v35, v42
	v_pk_mul_f32 v[18:19], v[18:19], v[40:41]
	v_mov_b32_e32 v33, v46
	v_pk_mul_f32 v[16:17], v[16:17], v[44:45]
	v_mul_f32_e32 v14, v14, v48
	v_mul_f32_e32 v28, v28, v49
	v_mov_b32_e32 v15, v30
	v_mov_b32_e32 v29, v31
	v_pk_fma_f32 v[20:21], v[54:55], v[52:53], v[20:21]
	v_pk_fma_f32 v[18:19], v[36:37], v[34:35], v[18:19]
	v_pk_fma_f32 v[16:17], v[38:39], v[32:33], v[16:17]
	v_pk_add_f32 v[14:15], v[14:15], v[28:29]
	s_branch .LBB0_1648

; template <int DLEN, int LPR, int ROPE, bool KR>
; DI void norm_rows(half_t* base, int stride, int nrows, const float* gain, float oscale, const half_t* zmla, const float2* rtab, int wv_) {
;     ...
;   for (int r0 = (blockIdx.x * NWAVE + wave) * RPW; r0 < nrows; r0 += gridDim.x * NWAVE * RPW) {
;     const int rho = r0 + sub;
;     const int t = rho % TOK;
;     half_t* ptr = base + (size_t)rho * stride + s * 8;
;     const half_t* src = ptr;
;     if (KR && s >= 8) {
;       const int b = rho / (4 * TOK);
;       src = zmla + ((size_t)b * TOK + t) * ZS + 128 + (s - 8) * 8;
;     }
;     float f[8];
;     float ss = 0.f;
;     if (active) {
;       const h8 v = *(const h8*)src;
; #pragma unroll
;       for (int i = 0; i < 8; ++i) { f[i] = (float)v[i]; ss += f[i] * f[i]; }
;     } else {
; #pragma unroll
;       for (int i = 0; i < 8; ++i) f[i] = 0.f;
;     }
; #pragma unroll
;     for (int o = LPR / 2; o > 0; o >>= 1) ss += __shfl_xor(ss, o);
;     const float rstd = rsqrtf(ss * (1.f / DLEN) + EPS);
; #pragma unroll
;     for (int i = 0; i < 8; ++i) f[i] = f[i] * rstd * gn[i];
;     if (ROPE != 0) {
;       constexpr int PX = (ROPE == 64) ? 2 : 1;
;       float pf[8];
; #pragma unroll
;       for (int i = 0; i < 8; ++i) pf[i] = __shfl_xor(f[i], PX);
;       constexpr int RB = (DLEN - ROPE) / 8;
;       if (t < SEQ && s >= RB && active) {
;         const int sr = s - RB;
;         const int q = (ROPE == 64) ? (sr >> 1) : sr;
;         const int pos = (q < 2) ? (t >> 6) : (t & 63);
;         const float sgn = (q & 1) ? 1.f : -1.f;
;         constexpr int NFI = (ROPE == 64) ? 16 : 8;
;         const float2* tb = rtab + ((ROPE == 64) ? 512 : 0) + pos * NFI + ((ROPE == 64) ? (sr & 1) * 8 : 0);
; #pragma unroll
;         for (int i = 0; i < 8; ++i) {
;           const float2 cssn = tb[i];
;           f[i] = f[i] * cssn.x + sgn * pf[i] * cssn.y;
;         }
;       }
;     }
.LBB0_1654:
	v_add_u32_e32 v36, v22, v1
	v_ashrrev_i32_e32 v37, 31, v36
	v_lshlrev_b64 v[12:13], 7, v[36:37]
	v_lshl_add_u64 v[12:13], v[10:11], 0, v[12:13]
	global_load_dwordx4 v[14:17], v[12:13], off
	s_waitcnt vmcnt(0)
	v_cvt_f32_f16_e32 v18, v14
	v_cvt_f32_f16_sdwa v19, v14 dst_sel:DWORD dst_unused:UNUSED_PAD src0_sel:WORD_1
	v_cvt_f32_f16_e32 v14, v15
	v_cvt_f32_f16_sdwa v15, v15 dst_sel:DWORD dst_unused:UNUSED_PAD src0_sel:WORD_1
	v_cvt_f32_f16_e32 v20, v16
	v_cvt_f32_f16_sdwa v21, v16 dst_sel:DWORD dst_unused:UNUSED_PAD src0_sel:WORD_1
	v_pk_mul_f32 v[28:29], v[18:19], v[18:19]
	v_cvt_f32_f16_e32 v16, v17
	v_cvt_f32_f16_sdwa v17, v17 dst_sel:DWORD dst_unused:UNUSED_PAD src0_sel:WORD_1
	v_pk_mul_f32 v[30:31], v[14:15], v[14:15]
	s_waitcnt lgkmcnt(0)
	v_add_f32_e32 v27, v28, v29
	v_add_f32_e32 v27, v30, v27
	v_pk_mul_f32 v[32:33], v[20:21], v[20:21]
	v_add_f32_e32 v27, v31, v27
	v_add_f32_e32 v27, v32, v27
	v_pk_mul_f32 v[34:35], v[16:17], v[16:17]
	v_add_f32_e32 v27, v33, v27
	v_add_f32_e32 v27, v34, v27
	v_add_f32_e32 v27, v35, v27
	v_mul_hi_i32 v35, v36, s71
	v_lshrrev_b32_e32 v37, 31, v35
	v_ashrrev_i32_e32 v35, 9, v35
	v_add_u32_e32 v35, v35, v37
	s_waitcnt lgkmcnt(0)
	s_nop 1
	v_add_f32_dpp v27, v27, v27 row_half_mirror row_mask:0xf bank_mask:0xf
	v_mul_i32_i24_e32 v35, 0x900, v35
	v_sub_u32_e32 v35, v36, v35
	s_waitcnt lgkmcnt(0)
	s_nop 1
	v_add_f32_dpp v27, v27, v27 quad_perm:[2,3,0,1] row_mask:0xf bank_mask:0xf
	s_waitcnt lgkmcnt(0)
	s_nop 1
	v_add_f32_dpp v27, v27, v27 quad_perm:[1,0,3,2] row_mask:0xf bank_mask:0xf
	v_fmamk_f32 v27, v27, 0x3c800000, v222
	v_mul_f32_e32 v28, 0x4b800000, v27
	v_cmp_gt_f32_e64 s[4:5], s73, v27
	s_nop 1
	v_cndmask_b32_e64 v27, v27, v28, s[4:5]
	v_rsq_f32_e32 v27, v27
	s_nop 0
	v_mul_f32_e32 v28, 0x45800000, v27
	v_cndmask_b32_e64 v28, v27, v28, s[4:5]
	v_pk_mul_f32 v[18:19], v[28:29], v[18:19] op_sel_hi:[0,1]
	v_pk_mul_f32 v[14:15], v[28:29], v[14:15] op_sel_hi:[0,1]
	v_pk_mul_f32 v[30:31], v[28:29], v[20:21] op_sel_hi:[0,1]
	v_pk_mul_f32 v[28:29], v[28:29], v[16:17] op_sel_hi:[0,1]
	v_pk_mul_f32 v[20:21], v[6:7], v[18:19]
	v_pk_mul_f32 v[18:19], v[8:9], v[14:15]
	v_pk_mul_f32 v[16:17], v[2:3], v[30:31]
	v_pk_mul_f32 v[14:15], v[4:5], v[28:29]
	s_nop 1
	v_mov_b32_dpp v33, v20 quad_perm:[2,3,0,1] row_mask:0xf bank_mask:0xf
	v_mov_b32_dpp v34, v21 quad_perm:[2,3,0,1] row_mask:0xf bank_mask:0xf
	v_mov_b32_dpp v31, v18 quad_perm:[2,3,0,1] row_mask:0xf bank_mask:0xf
	v_mov_b32_dpp v32, v19 quad_perm:[2,3,0,1] row_mask:0xf bank_mask:0xf
	v_mov_b32_dpp v29, v16 quad_perm:[2,3,0,1] row_mask:0xf bank_mask:0xf
	v_mov_b32_dpp v30, v17 quad_perm:[2,3,0,1] row_mask:0xf bank_mask:0xf
	v_mov_b32_dpp v28, v14 quad_perm:[2,3,0,1] row_mask:0xf bank_mask:0xf
	v_mov_b32_dpp v27, v15 quad_perm:[2,3,0,1] row_mask:0xf bank_mask:0xf
	v_cmp_gt_i32_e64 s[4:5], s85, v35
	s_and_saveexec_b64 s[10:11], s[4:5]
	s_cbranch_execz .LBB0_1653
	v_lshrrev_b32_e32 v36, 6, v35
	v_and_b32_e32 v35, 63, v35
	v_cndmask_b32_e32 v35, v35, v36, vcc
	v_lshl_or_b32 v35, v35, 7, v24
	ds_read_b128 v[36:39], v35 offset:4096
	ds_read_b128 v[40:43], v35 offset:4112
	ds_read_b128 v[44:47], v35 offset:4128
	ds_read_b128 v[48:51], v35 offset:4144
	s_waitcnt lgkmcnt(11)
	v_cndmask_b32_e64 v54, v33, -v33, s[2:3]
	s_waitcnt lgkmcnt(10)
	v_cndmask_b32_e64 v33, v34, -v34, s[2:3]
	s_waitcnt lgkmcnt(3)
	v_mov_b32_e32 v52, v37
	v_mov_b32_e32 v55, v21
	v_mov_b32_e32 v21, v33
	v_mov_b32_e32 v37, v39
	v_pk_mul_f32 v[20:21], v[20:21], v[36:37]
	v_cndmask_b32_e64 v36, v31, -v31, s[2:3]
	v_cndmask_b32_e64 v31, v32, -v32, s[2:3]
	v_mov_b32_e32 v53, v38
	v_mov_b32_e32 v37, v19
	v_mov_b32_e32 v19, v31
	v_cndmask_b32_e64 v38, v29, -v29, s[2:3]
	v_cndmask_b32_e64 v29, v30, -v30, s[2:3]
	v_cndmask_b32_e64 v31, v27, -v27, s[2:3]
	v_mov_b32_e32 v30, v15
	s_waitcnt lgkmcnt(2)
	v_mov_b32_e32 v34, v41
	v_mov_b32_e32 v41, v43
	s_waitcnt lgkmcnt(1)
	v_mov_b32_e32 v32, v45
	v_mov_b32_e32 v39, v17
	v_mov_b32_e32 v17, v29
	v_mov_b32_e32 v45, v47
	v_cndmask_b32_e64 v28, v28, -v28, s[2:3]
	s_waitcnt lgkmcnt(0)
	v_pk_mul_f32 v[30:31], v[30:31], v[50:51]
	v_mov_b32_e32 v35, v42
	v_pk_mul_f32 v[18:19], v[18:19], v[40:41]
	v_mov_b32_e32 v33, v46
	v_pk_mul_f32 v[16:17], v[16:17], v[44:45]
	v_mul_f32_e32 v14, v14, v48
	v_mul_f32_e32 v28, v28, v49
	v_mov_b32_e32 v15, v30
	v_mov_b32_e32 v29, v31
	v_pk_fma_f32 v[20:21], v[54:55], v[52:53], v[20:21]
	v_pk_fma_f32 v[18:19], v[36:37], v[34:35], v[18:19]
	v_pk_fma_f32 v[16:17], v[38:39], v[32:33], v[16:17]
	v_pk_add_f32 v[14:15], v[14:15], v[28:29]
	s_branch .LBB0_1653

; DI unsigned xb_ld(unsigned* p) { return __hip_atomic_load(p, __ATOMIC_RELAXED, __HIP_MEMORY_SCOPE_AGENT); }
; DI unsigned xb_add(unsigned* p, unsigned v) { return __hip_atomic_fetch_add(p, v, __ATOMIC_RELAXED, __HIP_MEMORY_SCOPE_AGENT); }
; #define XB_SPIN(cond, bar) do { unsigned _sp = 0; while (cond) { __builtin_amdgcn_s_sleep(1); \
;     if ((++_sp & 255u) == 0u) { if (xb_ld(&(bar)[XB_TMO])) break; if (_sp > XB_SPIN_CAP) { atomicAdd(&(bar)[XB_TMO], 1u); break; } } } } while (0)
; DI void xcd_barrier(char* ws_, LAS unsigned char* lds_, int wv_) {
;     ...
;     const unsigned old = xb_add(&bar[XB_XSUB(x)], 1u);
;     const unsigned gen = old / nloc;
;     if (old + 1u == (gen + 1u) * nloc) {
;       __builtin_amdgcn_fence(__ATOMIC_RELEASE, "agent");
;       asm volatile("s_waitcnt vmcnt(0)" ::: "memory");
;       const unsigned og = xb_add(&bar[XB_TOP], 1u);
;       const unsigned tg = og / nx;
;       if (og + 1u == (tg + 1u) * nx) xb_add(&bar[XB_TOPGEN], 1u);
;       else XB_SPIN(xb_ld(&bar[XB_TOPGEN]) == tg, bar);
;       __builtin_amdgcn_fence(__ATOMIC_ACQUIRE, "agent");
;       xb_add(&bar[XB_XGEN(x)], 1u);
;       asm volatile("s_waitcnt vmcnt(0)" ::: "memory");
;     } else {
;       XB_SPIN(xb_ld(&bar[XB_XGEN(x)]) == gen, bar);
.LBB0_1671:
	s_lshl_b32 s2, s37, 8
	s_add_u32 s23, s34, s2
	s_addc_u32 s22, s35, 0
	v_mov_b32_e32 v1, s23
	v_add_co_u32_e32 v6, vcc, 0x1000, v1
	v_mov_b32_e32 v1, s22
	s_nop 0
	v_addc_co_u32_e32 v7, vcc, 0, v1, vcc
	flat_atomic_add v3, v[6:7], v225 offset:1024 sc0
	v_cvt_f32_u32_e32 v1, v4
	v_sub_u32_e32 v5, 0, v4
	v_rcp_iflag_f32_e32 v1, v1
	s_nop 0
	v_mul_f32_e32 v1, 0x4f7ffffe, v1
	v_cvt_u32_f32_e32 v1, v1
	v_mul_lo_u32 v5, v5, v1
	v_mul_hi_u32 v5, v1, v5
	v_add_u32_e32 v1, v1, v5
	s_waitcnt vmcnt(0) lgkmcnt(0)
	v_mul_hi_u32 v1, v3, v1
	v_mul_lo_u32 v5, v1, v4
	v_sub_u32_e32 v5, v3, v5
	v_cmp_ge_u32_e32 vcc, v5, v4
	v_add_u32_e32 v6, 1, v1
	v_add_u32_e32 v3, 1, v3
	v_cndmask_b32_e32 v1, v1, v6, vcc
	v_sub_u32_e32 v6, v5, v4
	v_cndmask_b32_e32 v5, v5, v6, vcc
	v_cmp_ge_u32_e32 vcc, v5, v4
	v_add_u32_e32 v5, 1, v1
	s_nop 0
	v_cndmask_b32_e32 v1, v1, v5, vcc
	v_mad_u64_u32 v[4:5], s[2:3], v4, v1, v[4:5]
	v_cmp_ne_u32_e32 vcc, v3, v4
	s_and_saveexec_b64 s[2:3], vcc
	s_xor_b64 s[2:3], exec, s[2:3]
	s_cbranch_execz .LBB0_1684
	s_add_u32 s6, s34, 0x3500
	s_addc_u32 s7, s35, 0
	v_mov_b32_e32 v2, s6
	v_mov_b32_e32 v3, s7
	flat_load_dword v2, v[2:3] sc1
	s_waitcnt vmcnt(0) lgkmcnt(0)
	v_cmp_eq_u32_e32 vcc, v2, v1
	s_and_saveexec_b64 s[4:5], vcc
	s_cbranch_execz .LBB0_1683
	s_mov_b32 s24, 1
	s_mov_b64 s[8:9], 0
	s_branch .LBB0_1675

; template <int DLEN, int LPR, int ROPE, bool KR>
; DI void norm_rows(half_t* base, int stride, int nrows, const float* gain, float oscale, const half_t* zmla, const float2* rtab, int wv_) {
;     ...
;     for (int o = LPR / 2; o > 0; o >>= 1) ss += __shfl_xor(ss, o);
;     const float rstd = rsqrtf(ss * (1.f / DLEN) + EPS);
; #pragma unroll
;     for (int i = 0; i < 8; ++i) f[i] = f[i] * rstd * gn[i];
;     if (ROPE != 0) {
;       constexpr int PX = (ROPE == 64) ? 2 : 1;
;       float pf[8];
; #pragma unroll
;       for (int i = 0; i < 8; ++i) pf[i] = __shfl_xor(f[i], PX);
;       constexpr int RB = (DLEN - ROPE) / 8;
;       if (t < SEQ && s >= RB && active) {
;         const int sr = s - RB;
;         const int q = (ROPE == 64) ? (sr >> 1) : sr;
;         const int pos = (q < 2) ? (t >> 6) : (t & 63);
;         const float sgn = (q & 1) ? 1.f : -1.f;
;         constexpr int NFI = (ROPE == 64) ? 16 : 8;
;         const float2* tb = rtab + ((ROPE == 64) ? 512 : 0) + pos * NFI + ((ROPE == 64) ? (sr & 1) * 8 : 0);
; #pragma unroll
;         for (int i = 0; i < 8; ++i) {
;           const float2 cssn = tb[i];
;           f[i] = f[i] * cssn.x + sgn * pf[i] * cssn.y;
;         }
;       }
;     }
.LBB0_1824:
	s_or_b64 exec, exec, s[8:9]
	v_mul_hi_i32 v29, v27, s71
	v_lshrrev_b32_e32 v30, 31, v29
	v_ashrrev_i32_e32 v29, 9, v29
	v_add_u32_e32 v29, v29, v30
	v_mul_i32_i24_e32 v29, 0x900, v29
	v_sub_u32_e32 v27, v27, v29
	s_waitcnt lgkmcnt(0)
	s_nop 1
	v_add_f32_dpp v28, v28, v28 row_mirror row_mask:0xf bank_mask:0xf
	s_waitcnt lgkmcnt(0)
	s_nop 1
	v_add_f32_dpp v28, v28, v28 row_half_mirror row_mask:0xf bank_mask:0xf
	s_waitcnt lgkmcnt(0)
	s_nop 1
	v_add_f32_dpp v28, v28, v28 quad_perm:[2,3,0,1] row_mask:0xf bank_mask:0xf
	s_waitcnt lgkmcnt(0)
	s_nop 1
	v_add_f32_dpp v28, v28, v28 quad_perm:[1,0,3,2] row_mask:0xf bank_mask:0xf
	v_fmamk_f32 v28, v28, 0x3c2aaaab, v222
	v_cmp_gt_f32_e64 s[8:9], s73, v28
	v_mul_f32_e32 v29, 0x4b800000, v28
	s_nop 0
	v_cndmask_b32_e64 v28, v28, v29, s[8:9]
	v_rsq_f32_e32 v28, v28
	s_nop 0
	v_mul_f32_e32 v29, 0x45800000, v28
	v_cndmask_b32_e64 v28, v28, v29, s[8:9]
	v_pk_mul_f32 v[20:21], v[20:21], v[28:29] op_sel_hi:[1,0]
	v_pk_mul_f32 v[18:19], v[18:19], v[28:29] op_sel_hi:[1,0]
	v_pk_mul_f32 v[14:15], v[14:15], v[28:29] op_sel_hi:[1,0]
	v_pk_mul_f32 v[16:17], v[16:17], v[28:29] op_sel_hi:[1,0]
	s_waitcnt vmcnt(0)
	v_pk_mul_f32 v[20:21], v[2:3], v[20:21]
	v_pk_mul_f32 v[18:19], v[4:5], v[18:19]
	v_pk_mul_f32 v[14:15], v[6:7], v[14:15]
	v_pk_mul_f32 v[16:17], v[8:9], v[16:17]
	s_nop 1
	v_mov_b32_dpp v34, v20 quad_perm:[1,0,3,2] row_mask:0xf bank_mask:0xf
	v_mov_b32_dpp v35, v21 quad_perm:[1,0,3,2] row_mask:0xf bank_mask:0xf
	v_mov_b32_dpp v32, v18 quad_perm:[1,0,3,2] row_mask:0xf bank_mask:0xf
	v_mov_b32_dpp v33, v19 quad_perm:[1,0,3,2] row_mask:0xf bank_mask:0xf
	v_mov_b32_dpp v30, v14 quad_perm:[1,0,3,2] row_mask:0xf bank_mask:0xf
	v_mov_b32_dpp v31, v15 quad_perm:[1,0,3,2] row_mask:0xf bank_mask:0xf
	v_mov_b32_dpp v28, v16 quad_perm:[1,0,3,2] row_mask:0xf bank_mask:0xf
	v_mov_b32_dpp v29, v17 quad_perm:[1,0,3,2] row_mask:0xf bank_mask:0xf
	v_cmp_gt_i32_e64 s[8:9], s85, v27
	s_and_b64 s[16:17], s[2:3], s[8:9]
	s_and_saveexec_b64 s[8:9], s[16:17]
	s_cbranch_execz .LBB0_1826
	v_lshrrev_b32_e32 v36, 6, v27
	v_and_b32_e32 v27, 63, v27
	v_cndmask_b32_e64 v27, v27, v36, s[4:5]
	v_lshlrev_b32_e32 v27, 6, v27
	ds_read_b128 v[36:39], v27
	ds_read_b128 v[40:43], v27 offset:16
	ds_read_b128 v[44:47], v27 offset:32
	ds_read_b128 v[48:51], v27 offset:48
	s_waitcnt lgkmcnt(10)
	v_cndmask_b32_e64 v27, v35, -v35, s[6:7]
	s_waitcnt lgkmcnt(3)
	v_mov_b32_e32 v52, v37
	v_mov_b32_e32 v35, v21
	v_mov_b32_e32 v21, v27
	v_mov_b32_e32 v37, v39
	v_cndmask_b32_e64 v27, v33, -v33, s[6:7]
	v_pk_mul_f32 v[20:21], v[20:21], v[36:37]
	s_waitcnt lgkmcnt(2)
	v_mov_b32_e32 v36, v41
	v_mov_b32_e32 v33, v19
	v_mov_b32_e32 v19, v27
	v_mov_b32_e32 v41, v43
	v_pk_mul_f32 v[18:19], v[18:19], v[40:41]
	v_cndmask_b32_e64 v27, v31, -v31, s[6:7]
	v_cndmask_b32_e64 v41, v29, -v29, s[6:7]
	v_mov_b32_e32 v40, v17
	v_mov_b32_e32 v53, v38
	s_waitcnt lgkmcnt(1)
	v_mov_b32_e32 v38, v45
	v_mov_b32_e32 v31, v15
	v_mov_b32_e32 v15, v27
	v_mov_b32_e32 v45, v47
	v_cndmask_b32_e64 v27, v28, -v28, s[6:7]
	s_waitcnt lgkmcnt(0)
	v_pk_mul_f32 v[40:41], v[40:41], v[50:51]
	v_cndmask_b32_e64 v34, v34, -v34, s[6:7]
	v_mov_b32_e32 v37, v42
	v_cndmask_b32_e64 v32, v32, -v32, s[6:7]
	v_mov_b32_e32 v39, v46
	v_cndmask_b32_e64 v30, v30, -v30, s[6:7]
	v_pk_mul_f32 v[14:15], v[14:15], v[44:45]
	v_mul_f32_e32 v16, v16, v48
	v_mul_f32_e32 v28, v27, v49
	v_mov_b32_e32 v17, v40
	v_mov_b32_e32 v29, v41
	v_pk_fma_f32 v[20:21], v[34:35], v[52:53], v[20:21]
	v_pk_fma_f32 v[18:19], v[32:33], v[36:37], v[18:19]
	v_pk_fma_f32 v[14:15], v[30:31], v[38:39], v[14:15]
	v_pk_add_f32 v[16:17], v[16:17], v[28:29]

; template <int DLEN, int LPR, int ROPE, bool KR>
; DI void norm_rows(half_t* base, int stride, int nrows, const float* gain, float oscale, const half_t* zmla, const float2* rtab, int wv_) {
;     ...
;     for (int o = LPR / 2; o > 0; o >>= 1) ss += __shfl_xor(ss, o);
;     const float rstd = rsqrtf(ss * (1.f / DLEN) + EPS);
; #pragma unroll
;     for (int i = 0; i < 8; ++i) f[i] = f[i] * rstd * gn[i];
;     if (ROPE != 0) {
;       constexpr int PX = (ROPE == 64) ? 2 : 1;
;       float pf[8];
; #pragma unroll
;       for (int i = 0; i < 8; ++i) pf[i] = __shfl_xor(f[i], PX);
;       constexpr int RB = (DLEN - ROPE) / 8;
;       if (t < SEQ && s >= RB && active) {
;         const int sr = s - RB;
;         const int q = (ROPE == 64) ? (sr >> 1) : sr;
;         const int pos = (q < 2) ? (t >> 6) : (t & 63);
;         const float sgn = (q & 1) ? 1.f : -1.f;
;         constexpr int NFI = (ROPE == 64) ? 16 : 8;
;         const float2* tb = rtab + ((ROPE == 64) ? 512 : 0) + pos * NFI + ((ROPE == 64) ? (sr & 1) * 8 : 0);
; #pragma unroll
;         for (int i = 0; i < 8; ++i) {
;           const float2 cssn = tb[i];
;           f[i] = f[i] * cssn.x + sgn * pf[i] * cssn.y;
;         }
;       }
;     }
.LBB0_1851:
	s_or_b64 exec, exec, s[10:11]
	s_waitcnt lgkmcnt(0)
	s_nop 1
	v_add_f32_dpp v17, v17, v17 row_mirror row_mask:0xf bank_mask:0xf
	s_waitcnt lgkmcnt(0)
	s_nop 1
	v_add_f32_dpp v17, v17, v17 row_half_mirror row_mask:0xf bank_mask:0xf
	s_waitcnt lgkmcnt(0)
	s_nop 1
	v_add_f32_dpp v17, v17, v17 quad_perm:[2,3,0,1] row_mask:0xf bank_mask:0xf
	s_waitcnt lgkmcnt(0)
	s_nop 1
	v_add_f32_dpp v17, v17, v17 quad_perm:[1,0,3,2] row_mask:0xf bank_mask:0xf
	v_fmamk_f32 v17, v17, 0x3c2aaaab, v222
	v_mul_f32_e32 v26, 0x4b800000, v17
	v_cmp_gt_f32_e64 s[10:11], s73, v17
	s_nop 1
	v_cndmask_b32_e64 v17, v17, v26, s[10:11]
	v_rsq_f32_e32 v17, v17
	s_nop 0
	v_mul_f32_e32 v26, 0x45800000, v17
	v_cndmask_b32_e64 v26, v17, v26, s[10:11]
	v_pk_mul_f32 v[18:19], v[18:19], v[26:27] op_sel_hi:[1,0]
	v_pk_mul_f32 v[20:21], v[20:21], v[26:27] op_sel_hi:[1,0]
	v_pk_mul_f32 v[34:35], v[24:25], v[26:27] op_sel_hi:[1,0]
	v_pk_mul_f32 v[26:27], v[22:23], v[26:27] op_sel_hi:[1,0]
	s_waitcnt vmcnt(0)
	v_pk_mul_f32 v[24:25], v[2:3], v[18:19]
	v_pk_mul_f32 v[22:23], v[4:5], v[20:21]
	v_pk_mul_f32 v[20:21], v[6:7], v[34:35]
	v_pk_mul_f32 v[18:19], v[8:9], v[26:27]
	s_nop 1
	v_mov_b32_dpp v36, v24 quad_perm:[1,0,3,2] row_mask:0xf bank_mask:0xf
	v_mov_b32_dpp v37, v25 quad_perm:[1,0,3,2] row_mask:0xf bank_mask:0xf
	v_mov_b32_dpp v34, v22 quad_perm:[1,0,3,2] row_mask:0xf bank_mask:0xf
	v_mov_b32_dpp v35, v23 quad_perm:[1,0,3,2] row_mask:0xf bank_mask:0xf
	v_mov_b32_dpp v27, v20 quad_perm:[1,0,3,2] row_mask:0xf bank_mask:0xf
	v_mov_b32_dpp v33, v21 quad_perm:[1,0,3,2] row_mask:0xf bank_mask:0xf
	v_mov_b32_dpp v17, v18 quad_perm:[1,0,3,2] row_mask:0xf bank_mask:0xf
	v_mov_b32_dpp v26, v19 quad_perm:[1,0,3,2] row_mask:0xf bank_mask:0xf
	v_cmp_gt_i32_e64 s[10:11], s85, v16
	s_and_b64 s[16:17], s[8:9], s[10:11]
	s_and_saveexec_b64 s[10:11], s[16:17]
	s_cbranch_execz .LBB0_1853
	v_lshrrev_b32_e32 v38, 6, v16
	v_and_b32_e32 v16, 63, v16
	v_cndmask_b32_e64 v16, v16, v38, s[4:5]
	v_lshlrev_b32_e32 v16, 6, v16
	ds_read_b128 v[38:41], v16
	ds_read_b128 v[42:45], v16 offset:16
	ds_read_b128 v[46:49], v16 offset:32
	ds_read_b128 v[50:53], v16 offset:48
	s_waitcnt lgkmcnt(10)
	v_cndmask_b32_e64 v16, v37, -v37, s[6:7]
	s_waitcnt lgkmcnt(3)
	v_mov_b32_e32 v54, v39
	v_mov_b32_e32 v37, v25
	v_mov_b32_e32 v25, v16
	v_mov_b32_e32 v39, v41
	v_cndmask_b32_e64 v16, v35, -v35, s[6:7]
	v_pk_mul_f32 v[24:25], v[24:25], v[38:39]
	s_waitcnt lgkmcnt(2)
	v_mov_b32_e32 v38, v43
	v_mov_b32_e32 v35, v23
	v_mov_b32_e32 v23, v16
	v_mov_b32_e32 v43, v45
	v_pk_mul_f32 v[22:23], v[22:23], v[42:43]
	v_cndmask_b32_e64 v42, v27, -v27, s[6:7]
	v_cndmask_b32_e64 v16, v33, -v33, s[6:7]
	v_cndmask_b32_e64 v27, v26, -v26, s[6:7]
	v_mov_b32_e32 v26, v19
	v_mov_b32_e32 v55, v40
	s_waitcnt lgkmcnt(1)
	v_mov_b32_e32 v40, v47
	v_mov_b32_e32 v43, v21
	v_mov_b32_e32 v21, v16
	v_mov_b32_e32 v47, v49
	v_cndmask_b32_e64 v17, v17, -v17, s[6:7]
	s_waitcnt lgkmcnt(0)
	v_pk_mul_f32 v[26:27], v[26:27], v[52:53]
	v_cndmask_b32_e64 v36, v36, -v36, s[6:7]
	v_mov_b32_e32 v39, v44
	v_cndmask_b32_e64 v34, v34, -v34, s[6:7]
	v_mov_b32_e32 v41, v48
	v_pk_mul_f32 v[20:21], v[20:21], v[46:47]
	v_mul_f32_e32 v16, v18, v50
	v_mul_f32_e32 v18, v17, v51
	v_mov_b32_e32 v17, v26
	v_mov_b32_e32 v19, v27
	v_pk_fma_f32 v[24:25], v[36:37], v[54:55], v[24:25]
	v_pk_fma_f32 v[22:23], v[34:35], v[38:39], v[22:23]
	v_pk_fma_f32 v[20:21], v[42:43], v[40:41], v[20:21]
	v_pk_add_f32 v[18:19], v[16:17], v[18:19]

; DI unsigned xb_ld(unsigned* p) { return __hip_atomic_load(p, __ATOMIC_RELAXED, __HIP_MEMORY_SCOPE_AGENT); }
; DI unsigned xb_add(unsigned* p, unsigned v) { return __hip_atomic_fetch_add(p, v, __ATOMIC_RELAXED, __HIP_MEMORY_SCOPE_AGENT); }
; #define XB_SPIN(cond, bar) do { unsigned _sp = 0; while (cond) { __builtin_amdgcn_s_sleep(1); \
;     if ((++_sp & 255u) == 0u) { if (xb_ld(&(bar)[XB_TMO])) break; if (_sp > XB_SPIN_CAP) { atomicAdd(&(bar)[XB_TMO], 1u); break; } } } } while (0)
; DI void xcd_barrier(char* ws_, LAS unsigned char* lds_, int wv_) {
;     ...
;     const unsigned old = xb_add(&bar[XB_XSUB(x)], 1u);
;     const unsigned gen = old / nloc;
;     if (old + 1u == (gen + 1u) * nloc) {
;       __builtin_amdgcn_fence(__ATOMIC_RELEASE, "agent");
;       asm volatile("s_waitcnt vmcnt(0)" ::: "memory");
;       const unsigned og = xb_add(&bar[XB_TOP], 1u);
;       const unsigned tg = og / nx;
;       if (og + 1u == (tg + 1u) * nx) xb_add(&bar[XB_TOPGEN], 1u);
;       else XB_SPIN(xb_ld(&bar[XB_TOPGEN]) == tg, bar);
;       __builtin_amdgcn_fence(__ATOMIC_ACQUIRE, "agent");
;       xb_add(&bar[XB_XGEN(x)], 1u);
;       asm volatile("s_waitcnt vmcnt(0)" ::: "memory");
;     } else {
;       XB_SPIN(xb_ld(&bar[XB_XGEN(x)]) == gen, bar);
.LBB0_2227:
	s_lshl_b32 s2, s46, 8
	s_add_u32 s23, s34, s2
	s_addc_u32 s22, s35, 0
	v_mov_b32_e32 v1, s23
	v_add_co_u32_e32 v6, vcc, 0x1000, v1
	v_mov_b32_e32 v1, s22
	s_nop 0
	v_addc_co_u32_e32 v7, vcc, 0, v1, vcc
	flat_atomic_add v3, v[6:7], v225 offset:1024 sc0
	v_cvt_f32_u32_e32 v1, v4
	v_sub_u32_e32 v5, 0, v4
	v_rcp_iflag_f32_e32 v1, v1
	s_nop 0
	v_mul_f32_e32 v1, 0x4f7ffffe, v1
	v_cvt_u32_f32_e32 v1, v1
	v_mul_lo_u32 v5, v5, v1
	v_mul_hi_u32 v5, v1, v5
	v_add_u32_e32 v1, v1, v5
	s_waitcnt vmcnt(0) lgkmcnt(0)
	v_mul_hi_u32 v1, v3, v1
	v_mul_lo_u32 v5, v1, v4
	v_sub_u32_e32 v5, v3, v5
	v_cmp_ge_u32_e32 vcc, v5, v4
	v_add_u32_e32 v6, 1, v1
	v_add_u32_e32 v3, 1, v3
	v_cndmask_b32_e32 v1, v1, v6, vcc
	v_sub_u32_e32 v6, v5, v4
	v_cndmask_b32_e32 v5, v5, v6, vcc
	v_cmp_ge_u32_e32 vcc, v5, v4
	v_add_u32_e32 v5, 1, v1
	s_nop 0
	v_cndmask_b32_e32 v1, v1, v5, vcc
	v_mad_u64_u32 v[4:5], s[2:3], v4, v1, v[4:5]
	v_cmp_ne_u32_e32 vcc, v3, v4
	s_and_saveexec_b64 s[2:3], vcc
	s_xor_b64 s[2:3], exec, s[2:3]
	s_cbranch_execz .LBB0_2240
	s_add_u32 s6, s34, 0x3500
	s_addc_u32 s7, s35, 0
	v_mov_b32_e32 v2, s6
	v_mov_b32_e32 v3, s7
	flat_load_dword v2, v[2:3] sc1
	s_waitcnt vmcnt(0) lgkmcnt(0)
	v_cmp_eq_u32_e32 vcc, v2, v1
	s_and_saveexec_b64 s[4:5], vcc
	s_cbranch_execz .LBB0_2239
	s_mov_b32 s24, 1
	s_mov_b64 s[8:9], 0
	s_branch .LBB0_2231

; DI unsigned xb_ld(unsigned* p) { return __hip_atomic_load(p, __ATOMIC_RELAXED, __HIP_MEMORY_SCOPE_AGENT); }
; DI unsigned xb_add(unsigned* p, unsigned v) { return __hip_atomic_fetch_add(p, v, __ATOMIC_RELAXED, __HIP_MEMORY_SCOPE_AGENT); }
; #define XB_SPIN(cond, bar) do { unsigned _sp = 0; while (cond) { __builtin_amdgcn_s_sleep(1); \
;     if ((++_sp & 255u) == 0u) { if (xb_ld(&(bar)[XB_TMO])) break; if (_sp > XB_SPIN_CAP) { atomicAdd(&(bar)[XB_TMO], 1u); break; } } } } while (0)
; DI void xcd_barrier(char* ws_, LAS unsigned char* lds_, int wv_) {
;     ...
;     const unsigned old = xb_add(&bar[XB_XSUB(x)], 1u);
;     const unsigned gen = old / nloc;
;     if (old + 1u == (gen + 1u) * nloc) {
;       __builtin_amdgcn_fence(__ATOMIC_RELEASE, "agent");
;       asm volatile("s_waitcnt vmcnt(0)" ::: "memory");
;       const unsigned og = xb_add(&bar[XB_TOP], 1u);
;       const unsigned tg = og / nx;
;       if (og + 1u == (tg + 1u) * nx) xb_add(&bar[XB_TOPGEN], 1u);
;       else XB_SPIN(xb_ld(&bar[XB_TOPGEN]) == tg, bar);
;       __builtin_amdgcn_fence(__ATOMIC_ACQUIRE, "agent");
;       xb_add(&bar[XB_XGEN(x)], 1u);
;       asm volatile("s_waitcnt vmcnt(0)" ::: "memory");
;     } else {
;       XB_SPIN(xb_ld(&bar[XB_XGEN(x)]) == gen, bar);
.LBB0_2686:
	s_lshl_b32 s2, s40, 8
	s_add_u32 s23, s34, s2
	s_addc_u32 s22, s35, 0
	v_mov_b32_e32 v1, s23
	v_add_co_u32_e32 v6, vcc, 0x1000, v1
	v_mov_b32_e32 v1, s22
	s_nop 0
	v_addc_co_u32_e32 v7, vcc, 0, v1, vcc
	flat_atomic_add v3, v[6:7], v225 offset:1024 sc0
	v_cvt_f32_u32_e32 v1, v4
	v_sub_u32_e32 v5, 0, v4
	v_rcp_iflag_f32_e32 v1, v1
	s_nop 0
	v_mul_f32_e32 v1, 0x4f7ffffe, v1
	v_cvt_u32_f32_e32 v1, v1
	v_mul_lo_u32 v5, v5, v1
	v_mul_hi_u32 v5, v1, v5
	v_add_u32_e32 v1, v1, v5
	s_waitcnt vmcnt(0) lgkmcnt(0)
	v_mul_hi_u32 v1, v3, v1
	v_mul_lo_u32 v5, v1, v4
	v_sub_u32_e32 v5, v3, v5
	v_cmp_ge_u32_e32 vcc, v5, v4
	v_add_u32_e32 v6, 1, v1
	v_add_u32_e32 v3, 1, v3
	v_cndmask_b32_e32 v1, v1, v6, vcc
	v_sub_u32_e32 v6, v5, v4
	v_cndmask_b32_e32 v5, v5, v6, vcc
	v_cmp_ge_u32_e32 vcc, v5, v4
	v_add_u32_e32 v5, 1, v1
	s_nop 0
	v_cndmask_b32_e32 v1, v1, v5, vcc
	v_mad_u64_u32 v[4:5], s[2:3], v4, v1, v[4:5]
	v_cmp_ne_u32_e32 vcc, v3, v4
	s_and_saveexec_b64 s[2:3], vcc
	s_xor_b64 s[2:3], exec, s[2:3]
	s_cbranch_execz .LBB0_2699
	s_add_u32 s6, s34, 0x3500
	s_addc_u32 s7, s35, 0
	v_mov_b32_e32 v2, s6
	v_mov_b32_e32 v3, s7
	flat_load_dword v2, v[2:3] sc1
	s_waitcnt vmcnt(0) lgkmcnt(0)
	v_cmp_eq_u32_e32 vcc, v2, v1
	s_and_saveexec_b64 s[4:5], vcc
	s_cbranch_execz .LBB0_2698
	s_mov_b32 s24, 1
	s_mov_b64 s[8:9], 0
	s_branch .LBB0_2690
